# retention scan items drawn from per-XCD queues so the eight items sharing one K^T run on one XCD (L2 reuse)
# baseline (speedup 1.0000x reference)
; #define LAS __attribute__((address_space(3)))
; DI int otid() { int t = threadIdx.x; asm volatile("" : "+v"(t)); return t; }
; DI void phase_ret_scan(const Params& p, int l, LAS unsigned char* lds) {
;     const int tid = otid(), lane = tid & 63, wid = tid >> 6, r16 = lane & 15, q4 = lane >> 4;
;     unsigned char* ws = p.ws;
;     volatile LAS int* slot = (volatile LAS int*)(lds + LDS_CTRL + 64);
;     unsigned* ctr = (unsigned*)(ws + WS_QCTR + 256 * (3 + l));
;     constexpr int VRS = RB * 2 + 16;
;     for (;;) {
;         const int it = next_item(ctr, slot);
;         if (it >= 320) break;
;         const int dvb = it & 7, dir = (it >> 3) & 1, h = (it >> 4) % 5, b = it / 80, dkb = wid;
;         {
;             const bf16_t* vsrc = (const bf16_t*)(ws + WS_VTR) + ((size_t)b * 640 + h * 128 + dvb * 16) * RB;
;             u32x4 t[9];
; #pragma unroll
;             for (int i = 0; i < 9; ++i) { const int cid = tid + i * 512, rr = cid / 288, cc = cid % 288; t[i] = *(const u32x4*)(vsrc + (size_t)rr * RB + cc * 8); }
; #pragma unroll
;             for (int i = 0; i < 9; ++i) { const int cid = tid + i * 512, rr = cid / 288, cc = cid % 288; *(LAS u32x4*)(lds + rr * VRS + cc * 16) = t[i]; }
.LBB0_1076:
	s_and_b32 s8, s26, 7
	s_lshl_b32 s8, s8, 8
	s_add_u32 s8, s8, 0x4800
	s_cmp_eq_u32 s33, 0x100
	s_cselect_b32 s8, s8, 0x4300
	s_add_u32 s8, s50, s8
	s_addc_u32 s9, s51, 0
	s_add_u32 s87, s50, 0x18d20000
	s_addc_u32 s91, s51, 0
	v_mov_b32_e32 v1, v202
	s_add_u32 s0, s50, 0x19860000
	s_addc_u32 s1, s51, 0
	v_bfe_u32 v0, v1, 4, 2
	v_lshlrev_b32_e32 v40, 4, v0
	v_mov_b32_e32 v41, 0
	v_writelane_b32 v253, s0, 21
	v_add_u32_e32 v4, 0x200, v1
	v_and_b32_e32 v86, 15, v1
	v_writelane_b32 v253, s1, 22
	v_lshl_add_u64 v[42:43], s[0:1], 0, v[40:41]
	s_mov_b32 s1, 0x38e38e39
	v_mul_hi_i32 v5, v4, s1
	v_lshrrev_b32_e32 v6, 31, v5
	v_ashrrev_i32_e32 v5, 6, v5
	v_add_u32_e32 v5, v5, v6
	v_mul_i32_i24_e32 v6, 0x120, v5
	v_sub_u32_e32 v4, v4, v6
	v_add_u32_e32 v6, 0x400, v1
	v_mul_hi_i32 v7, v6, s1
	v_lshrrev_b32_e32 v8, 31, v7
	v_ashrrev_i32_e32 v7, 6, v7
	v_add_u32_e32 v7, v7, v8
	v_mul_i32_i24_e32 v8, 0x120, v7
	v_sub_u32_e32 v6, v6, v8
	v_add_u32_e32 v8, 0x600, v1
	v_mul_hi_i32 v9, v8, s1
	v_lshrrev_b32_e32 v10, 31, v9
	v_ashrrev_i32_e32 v9, 6, v9
	v_add_u32_e32 v9, v9, v10
	v_mul_i32_i24_e32 v10, 0x120, v9
	v_sub_u32_e32 v8, v8, v10
	v_add_u32_e32 v10, 0x800, v1
	v_mul_hi_i32 v11, v10, s1
	v_lshrrev_b32_e32 v12, 31, v11
	v_ashrrev_i32_e32 v11, 6, v11
	v_add_u32_e32 v11, v11, v12
	v_mul_i32_i24_e32 v12, 0x120, v11
	v_sub_u32_e32 v10, v10, v12
	v_add_u32_e32 v12, 0xa00, v1
	v_mul_hi_i32 v13, v12, s1
	v_lshrrev_b32_e32 v14, 31, v13
	v_ashrrev_i32_e32 v13, 6, v13
	v_add_u32_e32 v13, v13, v14
	v_mul_i32_i24_e32 v14, 0x120, v13
	v_sub_u32_e32 v12, v12, v14
	v_add_u32_e32 v14, 0xc00, v1
	v_mul_hi_i32 v15, v14, s1
	v_lshrrev_b32_e32 v16, 31, v15
	v_ashrrev_i32_e32 v15, 6, v15
	v_ashrrev_i32_e32 v2, 2, v1
	v_add_u32_e32 v15, v15, v16
	v_and_b32_e32 v36, -16, v2
	v_mul_u32_u24_e32 v2, 0x1210, v86
	v_mul_i32_i24_e32 v16, 0x120, v15
	v_add3_u32 v88, 0, v2, v40
	v_mul_hi_i32 v2, v1, s1
	v_sub_u32_e32 v14, v14, v16
	v_add_u32_e32 v16, 0xe00, v1
	v_lshrrev_b32_e32 v3, 31, v2
	v_ashrrev_i32_e32 v2, 6, v2
	v_mul_hi_i32 v17, v16, s1
	v_add_u32_e32 v2, v2, v3
	v_lshrrev_b32_e32 v18, 31, v17
	v_ashrrev_i32_e32 v17, 6, v17
	v_mul_i32_i24_e32 v3, 0x120, v2
	v_add_u32_e32 v17, v17, v18
	v_sub_u32_e32 v3, v1, v3
	v_mul_i32_i24_e32 v18, 0x120, v17
	v_add_u32_e32 v1, 0x1000, v1
	v_sub_u32_e32 v16, v16, v18
	v_mul_hi_i32 v18, v1, s1
	v_lshrrev_b32_e32 v19, 31, v18
	v_ashrrev_i32_e32 v18, 6, v18
	v_add_u32_e32 v18, v18, v19
	v_mul_i32_i24_e32 v19, 0x120, v18
	s_movk_i32 s0, 0x1210
	v_sub_u32_e32 v1, v1, v19
	v_lshlrev_b32_e32 v87, 3, v0
	v_ashrrev_i32_e32 v37, 31, v36
	s_add_u32 s92, s50, 0x1fda0000
	v_lshlrev_b32_e32 v0, 2, v0
	v_mul_hi_i32_i24_e32 v45, 0x1200, v2
	v_mul_i32_i24_e32 v44, 0x1200, v2
	v_lshlrev_b32_e32 v46, 3, v3
	v_mul_hi_i32_i24_e32 v49, 0x1200, v5
	v_mul_i32_i24_e32 v48, 0x1200, v5
	v_lshlrev_b32_e32 v50, 3, v4
	v_mul_hi_i32_i24_e32 v53, 0x1200, v7
	v_mul_i32_i24_e32 v52, 0x1200, v7
	v_lshlrev_b32_e32 v54, 3, v6
	v_mul_hi_i32_i24_e32 v57, 0x1200, v9
	v_mul_i32_i24_e32 v56, 0x1200, v9
	v_lshlrev_b32_e32 v58, 3, v8
	v_mul_hi_i32_i24_e32 v61, 0x1200, v11
	v_mul_i32_i24_e32 v60, 0x1200, v11
	v_lshlrev_b32_e32 v62, 3, v10
	v_mul_hi_i32_i24_e32 v65, 0x1200, v13
	v_mul_i32_i24_e32 v64, 0x1200, v13
	v_lshlrev_b32_e32 v66, 3, v12
	v_mul_hi_i32_i24_e32 v69, 0x1200, v15
	v_mul_i32_i24_e32 v68, 0x1200, v15
	v_lshlrev_b32_e32 v70, 3, v14
	v_mul_hi_i32_i24_e32 v73, 0x1200, v17
	v_mul_i32_i24_e32 v72, 0x1200, v17
	v_lshlrev_b32_e32 v74, 3, v16
	v_mul_hi_i32_i24_e32 v77, 0x1200, v18
; #define LAS __attribute__((address_space(3)))
; DI float ret_lg2(const Params& p, int l, int dir, int h) { return log1pf(-exp2f(p.in[12][(l * 2 + dir) * 5 + h])) * 1.4426950408889634f; }
; DI void phase_ret_scan(const Params& p, int l, LAS unsigned char* lds) {
;     ...
;     unsigned* ctr = (unsigned*)(ws + WS_QCTR + 256 * (3 + l));
;     constexpr int VRS = RB * 2 + 16;
;     for (;;) {
;         const int it = next_item(ctr, slot);
;         if (it >= 320) break;
;         const int dvb = it & 7, dir = (it >> 3) & 1, h = (it >> 4) % 5, b = it / 80, dkb = wid;
;         {
;             const bf16_t* vsrc = (const bf16_t*)(ws + WS_VTR) + ((size_t)b * 640 + h * 128 + dvb * 16) * RB;
;             u32x4 t[9];
; #pragma unroll
;             for (int i = 0; i < 9; ++i) { const int cid = tid + i * 512, rr = cid / 288, cc = cid % 288; t[i] = *(const u32x4*)(vsrc + (size_t)rr * RB + cc * 8); }
; #pragma unroll
;             for (int i = 0; i < 9; ++i) { const int cid = tid + i * 512, rr = cid / 288, cc = cid % 288; *(LAS u32x4*)(lds + rr * VRS + cc * 16) = t[i]; }
;         }
;         const float lg = ret_lg2(p, l, dir, h), gL = exp2f(lg * 128.f);
;         float wt[4][8];
; #pragma unroll
;         for (int ks = 0; ks < 4; ++ks)
; #pragma unroll
;             for (int e = 0; e < 8; ++e) { const int pp = ks * 32 + q4 * 8 + e; wt[ks][e] = exp2f(lg * (float)(dir == 0 ? 127 - pp : pp)); }
;         const bf16_t* kt = (const bf16_t*)(ws + WS_KTR) + ((size_t)b * 640 + h * 128 + dkb * 16 + r16) * RB + q4 * 8;
;         const LAS unsigned char* vl = lds + r16 * VRS + q4 * 16;
;         bf16_t* sb = (bf16_t*)(ws + WS_S) + ((size_t)((b * 5 + h) * 2 + dir) * 18) * 16384 + (dvb * 16 + r16) * 128 + dkb * 16 + q4 * 4;
	v_mul_i32_i24_e32 v76, 0x1200, v18
	v_lshlrev_b32_e32 v78, 3, v1
	v_mad_i32_i24 v2, v2, s0, 0
	v_lshlrev_b32_e32 v3, 4, v3
	v_mad_i32_i24 v5, v5, s0, 0
	v_lshlrev_b32_e32 v4, 4, v4
	v_mad_i32_i24 v7, v7, s0, 0
	v_lshlrev_b32_e32 v6, 4, v6
	v_mad_i32_i24 v9, v9, s0, 0
	v_lshlrev_b32_e32 v8, 4, v8
	v_mad_i32_i24 v11, v11, s0, 0
	v_lshlrev_b32_e32 v10, 4, v10
	v_mad_i32_i24 v13, v13, s0, 0
	v_lshlrev_b32_e32 v12, 4, v12
	v_mad_i32_i24 v15, v15, s0, 0
	v_lshlrev_b32_e32 v14, 4, v14
	v_mad_i32_i24 v17, v17, s0, 0
	v_lshlrev_b32_e32 v16, 4, v16
	v_mad_i32_i24 v18, v18, s0, 0
	v_lshlrev_b32_e32 v1, 4, v1
	v_or_b32_e32 v38, v36, v86
	v_mov_b32_e32 v39, v37
	s_mov_b32 s11, 0
	s_addc_u32 s93, s51, 0
	s_movk_i32 s2, 0x1200
	v_ashrrev_i32_e32 v47, 31, v46
	v_ashrrev_i32_e32 v51, 31, v50
	v_ashrrev_i32_e32 v55, 31, v54
	v_ashrrev_i32_e32 v59, 31, v58
	v_ashrrev_i32_e32 v63, 31, v62
	v_ashrrev_i32_e32 v67, 31, v66
	v_ashrrev_i32_e32 v71, 31, v70
	v_ashrrev_i32_e32 v75, 31, v74
	v_ashrrev_i32_e32 v79, 31, v78
	v_xor_b32_e32 v89, 0x7f, v87
	v_or_b32_e32 v90, 1, v87
	v_xor_b32_e32 v91, 0x7e, v87
	v_or_b32_e32 v92, 2, v87
	v_xor_b32_e32 v93, 0x7d, v87
	v_or_b32_e32 v94, 3, v87
	v_xor_b32_e32 v95, 0x7c, v87
	v_or_b32_e32 v96, 4, v87
	v_xor_b32_e32 v97, 0x7b, v87
	v_or_b32_e32 v98, 5, v87
	v_xor_b32_e32 v99, 0x7a, v87
	v_or_b32_e32 v100, 6, v87
	v_xor_b32_e32 v101, 0x79, v87
	v_or_b32_e32 v102, 7, v87
	v_xor_b32_e32 v103, 0x78, v87
	v_or_b32_e32 v104, 32, v87
	v_xor_b32_e32 v105, 0x5f, v87
	v_or_b32_e32 v106, 33, v87
	v_xor_b32_e32 v107, 0x5e, v87
	v_or_b32_e32 v108, 34, v87
	v_xor_b32_e32 v109, 0x5d, v87
	v_or_b32_e32 v110, 35, v87
	v_xor_b32_e32 v111, 0x5c, v87
	v_or_b32_e32 v112, 36, v87
	v_xor_b32_e32 v113, 0x5b, v87
	v_or_b32_e32 v114, 37, v87
	v_xor_b32_e32 v115, 0x5a, v87
	v_or_b32_e32 v116, 38, v87
	v_xor_b32_e32 v117, 0x59, v87
	v_or_b32_e32 v118, 39, v87
	v_xor_b32_e32 v119, 0x58, v87
	v_or_b32_e32 v120, 64, v87
	v_xor_b32_e32 v121, 63, v87
	v_or_b32_e32 v122, 0x41, v87
	v_xor_b32_e32 v123, 62, v87
	v_or_b32_e32 v124, 0x42, v87
	v_xor_b32_e32 v125, 61, v87
	v_or_b32_e32 v126, 0x43, v87
	v_xor_b32_e32 v127, 60, v87
	v_or_b32_e32 v128, 0x44, v87
	v_xor_b32_e32 v129, 59, v87
	v_or_b32_e32 v130, 0x45, v87
	v_xor_b32_e32 v131, 58, v87
	v_or_b32_e32 v132, 0x46, v87
	v_xor_b32_e32 v133, 57, v87
	v_or_b32_e32 v134, 0x47, v87
	v_xor_b32_e32 v135, 56, v87
	v_or_b32_e32 v136, 0x60, v87
	v_xor_b32_e32 v137, 31, v87
	v_or_b32_e32 v138, 0x61, v87
	v_xor_b32_e32 v139, 30, v87
	v_or_b32_e32 v140, 0x62, v87
	v_xor_b32_e32 v141, 29, v87
	v_or_b32_e32 v142, 0x63, v87
	v_xor_b32_e32 v143, 28, v87
	v_or_b32_e32 v144, 0x64, v87
	v_xor_b32_e32 v145, 27, v87
	v_or_b32_e32 v146, 0x65, v87
	v_xor_b32_e32 v147, 26, v87
	v_or_b32_e32 v148, 0x66, v87
	v_xor_b32_e32 v149, 25, v87
	v_or_b32_e32 v150, 0x67, v87
	v_xor_b32_e32 v151, 24, v87
	s_add_i32 s3, 0, 0x22040
	s_cmp_eq_u32 s33, 0x100
	s_cselect_b32 s4, 39, 0x13f
	v_add_u32_e32 v152, v2, v3
	v_add_u32_e32 v153, v5, v4
	v_add_u32_e32 v154, v7, v6
	v_add_u32_e32 v155, v9, v8
	v_add_u32_e32 v156, v11, v10
	v_add_u32_e32 v157, v13, v12
	v_add_u32_e32 v158, v15, v14
	v_add_u32_e32 v159, v17, v16
	v_add_u32_e32 v160, v18, v1
	s_mov_b32 s5, 0xc2fc0000
	s_mov_b32 s14, 0x3f2aaaab
	v_mov_b32_e32 v161, 0x3ecc95a3
	s_mov_b32 s15, 0x3f317218
	s_mov_b32 s16, 0x33800000
	v_lshlrev_b32_e32 v80, 1, v0
	v_mov_b32_e32 v162, 0x42800000
	v_mov_b32_e32 v82, 0x3f317218
	v_mov_b32_e32 v163, 0x7fc00000
	v_mov_b32_e32 v164, 0xff800000
	v_not_b32_e32 v165, 63
	s_branch .LBB0_1078

; #define LAS __attribute__((address_space(3)))
; DI unsigned xb_add(unsigned* p, unsigned v) { return __hip_atomic_fetch_add(p, v, __ATOMIC_RELAXED, __HIP_MEMORY_SCOPE_AGENT); }
; DI float ret_lg2(const Params& p, int l, int dir, int h) { return log1pf(-exp2f(p.in[12][(l * 2 + dir) * 5 + h])) * 1.4426950408889634f; }
; DI int next_item(unsigned* ctr, volatile LAS int* slot) {
;     __syncthreads();
;     if (threadIdx.x == 0) *slot = (int)xb_add(ctr, 1u);
;     __syncthreads();
;     return *slot;
; DI void phase_ret_scan(const Params& p, int l, LAS unsigned char* lds) {
;     ...
;     for (;;) {
;         const int it = next_item(ctr, slot);
;         if (it >= 320) break;
;         const int dvb = it & 7, dir = (it >> 3) & 1, h = (it >> 4) % 5, b = it / 80, dkb = wid;
;         {
;             const bf16_t* vsrc = (const bf16_t*)(ws + WS_VTR) + ((size_t)b * 640 + h * 128 + dvb * 16) * RB;
;             u32x4 t[9];
; #pragma unroll
;             for (int i = 0; i < 9; ++i) { const int cid = tid + i * 512, rr = cid / 288, cc = cid % 288; t[i] = *(const u32x4*)(vsrc + (size_t)rr * RB + cc * 8); }
; #pragma unroll
;             for (int i = 0; i < 9; ++i) { const int cid = tid + i * 512, rr = cid / 288, cc = cid % 288; *(LAS u32x4*)(lds + rr * VRS + cc * 16) = t[i]; }
;         }
;         const float lg = ret_lg2(p, l, dir, h), gL = exp2f(lg * 128.f);
.LBB0_1082:
	s_or_b64 exec, exec, s[0:1]
	s_waitcnt vmcnt(0)
	v_mov_b32_e32 v0, s3
	s_waitcnt lgkmcnt(0)
	s_barrier
	ds_read_b32 v0, v0
	s_mov_b64 s[0:1], -1
	s_waitcnt lgkmcnt(0)
	v_cmp_lt_i32_e32 vcc, s4, v0
	v_readfirstlane_b32 s10, v0
	s_cbranch_vccnz .LBB0_1077
	s_cmp_lg_u32 s33, 0x100
	s_cbranch_scc1 sx0_k
	s_and_b32 s0, s26, 7
	s_lshl_b32 s0, s0, 3
	s_lshr_b32 s1, s10, 3
	s_lshl_b32 s1, s1, 6
	s_and_b32 s10, s10, 7
	s_add_u32 s10, s10, s0
	s_add_u32 s10, s10, s1
sx0_k:
	s_ashr_i32 s0, s10, 4
	s_mul_hi_i32 s1, s0, 0x66666667
	s_lshr_b32 s6, s1, 31
	s_ashr_i32 s1, s1, 1
	s_add_i32 s1, s1, s6
	s_mul_i32 s1, s1, 5
	s_sub_i32 s6, s0, s1
	s_mul_hi_i32 s0, s10, 0x66666667
	s_lshr_b32 s1, s0, 31
	s_ashr_i32 s7, s0, 5
	s_add_i32 s7, s7, s1
	s_lshl_b32 s12, s6, 7
	s_mul_i32 s0, s7, 0x280
	s_ashr_i32 s13, s12, 31
	s_mul_hi_i32 s1, s7, 0x280
	s_add_u32 s0, s0, s12
	s_addc_u32 s1, s1, s13
	s_lshl_b32 s12, s10, 4
	s_and_b32 s17, s12, 0x70
	s_or_b32 s12, s0, s17
	s_mul_i32 s13, s1, 0x1200
	s_mul_hi_u32 s18, s12, 0x1200
	s_add_i32 s18, s18, s13
	s_mulk_i32 s12, 0x1200
	s_add_u32 s12, s87, s12
	s_addc_u32 s13, s91, s18
	s_bfe_u32 s10, s10, 0x10003
	v_lshl_add_u64 v[0:1], s[12:13], 0, v[44:45]
	v_lshl_add_u64 v[2:3], s[12:13], 0, v[48:49]
	v_lshl_add_u64 v[8:9], s[12:13], 0, v[52:53]
	s_mul_i32 s18, s10, 5
	v_lshl_add_u64 v[0:1], v[46:47], 1, v[0:1]
	v_lshl_add_u64 v[4:5], v[50:51], 1, v[2:3]
	v_lshl_add_u64 v[8:9], v[54:55], 1, v[8:9]
	v_lshl_add_u64 v[10:11], s[12:13], 0, v[56:57]
	s_add_i32 s18, s18, s6
	global_load_dwordx4 v[0:3], v[0:1], off
	s_nop 0
	global_load_dwordx4 v[4:7], v[4:5], off
	v_lshl_add_u64 v[10:11], v[58:59], 1, v[10:11]
	global_load_dwordx4 v[12:15], v[8:9], off
	global_load_dwordx4 v[16:19], v[10:11], off
	v_lshl_add_u64 v[8:9], s[12:13], 0, v[60:61]
	s_ashr_i32 s19, s18, 31
	v_lshl_add_u64 v[8:9], v[62:63], 1, v[8:9]
	v_lshl_add_u64 v[10:11], s[12:13], 0, v[64:65]
	s_lshl_b64 s[18:19], s[18:19], 2
	v_lshl_add_u64 v[10:11], v[66:67], 1, v[10:11]
	global_load_dwordx4 v[20:23], v[8:9], off
	global_load_dwordx4 v[24:27], v[10:11], off
	v_lshl_add_u64 v[8:9], s[12:13], 0, v[68:69]
	s_add_u32 s18, s60, s18
	v_lshl_add_u64 v[8:9], v[70:71], 1, v[8:9]
	v_lshl_add_u64 v[10:11], s[12:13], 0, v[72:73]
	s_addc_u32 s19, s61, s19
	v_lshl_add_u64 v[10:11], v[74:75], 1, v[10:11]
	global_load_dwordx4 v[28:31], v[8:9], off
	global_load_dwordx4 v[32:35], v[10:11], off
	global_load_dword v81, v41, s[18:19]
	v_lshl_add_u64 v[8:9], s[12:13], 0, v[76:77]
	v_lshl_add_u64 v[8:9], v[78:79], 1, v[8:9]
	global_load_dwordx4 v[8:11], v[8:9], off
	v_lshl_add_u64 v[166:167], v[38:39], 0, s[0:1]
	v_mad_u64_u32 v[84:85], s[0:1], v166, s2, v[42:43]
	v_mov_b32_e32 v40, v85
	v_mad_u64_u32 v[166:167], s[0:1], v167, s2, v[40:41]
	s_mul_i32 s7, s7, 5
	v_mov_b32_e32 v85, v166
	s_waitcnt vmcnt(0)
	ds_write_b128 v152, v[0:3]
	ds_write_b128 v153, v[4:7]
	ds_write_b128 v154, v[12:15]
	ds_write_b128 v155, v[16:19]
	ds_write_b128 v156, v[20:23]
	ds_write_b128 v157, v[24:27]
	ds_write_b128 v158, v[28:31]
	ds_write_b128 v159, v[32:35]
	v_cmp_gt_f32_e32 vcc, s5, v81
	s_and_b64 s[0:1], vcc, exec
	s_cselect_b32 s0, 0xffffffc0, 0
	v_cndmask_b32_e32 v0, 0, v162, vcc
	v_add_f32_e32 v0, v81, v0
	v_exp_f32_e32 v0, v0
	s_cmp_eq_u32 s10, 0
	s_cselect_b64 vcc, -1, 0
	s_add_i32 s7, s7, s6
	s_lshl_b32 s1, s7, 1
	s_or_b32 s1, s1, s10
	v_ldexp_f32 v22, v0, s0
	s_mul_hi_i32 s0, s1, 0x90000
	s_mul_i32 s1, s1, 0x90000
	v_sub_f32_e32 v6, 1.0, v22
	s_add_u32 s12, s92, s1
	v_add_f32_e32 v2, -1.0, v6
	v_frexp_mant_f32_e32 v7, v6
	v_cvt_f64_f32_e32 v[0:1], v6
	s_addc_u32 s13, s93, s0
	v_sub_f32_e32 v12, v2, v6
	v_frexp_exp_i32_f64_e32 v14, v[0:1]
	v_cmp_gt_f32_e64 s[0:1], s14, v7
	v_sub_f32_e64 v13, -v22, v2
	ds_write_b128 v160, v[8:11]
	v_add_f32_e32 v8, 1.0, v12
	v_subbrev_co_u32_e64 v14, s[0:1], 0, v14, s[0:1]
	v_add_f32_e32 v7, v13, v8
	v_sub_u32_e32 v8, 0, v14
	v_ldexp_f32 v6, v6, v8
	v_ldexp_f32 v7, v7, v8
	v_add_f32_e32 v8, -1.0, v6
	v_add_f32_e32 v9, 1.0, v6
	v_add_f32_e32 v10, 1.0, v8
	v_add_f32_e32 v11, -1.0, v9
	v_sub_f32_e32 v10, v6, v10
	v_sub_f32_e32 v6, v6, v11
	v_add_f32_e32 v6, v7, v6
	v_add_f32_e32 v15, v9, v6
	v_rcp_f32_e32 v17, v15
	v_add_f32_e32 v10, v7, v10
	v_sub_f32_e32 v7, v15, v9
	v_sub_f32_e32 v16, v6, v7
	v_add_f32_e32 v7, v8, v10
	v_mul_f32_e32 v19, v7, v17
	v_sub_f32_e32 v6, v7, v8
	v_mul_f32_e32 v8, v15, v19
	v_sub_f32_e32 v18, v10, v6
	v_fma_f32 v10, v19, v15, -v8
	v_fmac_f32_e32 v10, v19, v16
	v_add_f32_e32 v6, v8, v10
	v_sub_f32_e32 v9, v7, v6
	v_pk_add_f32 v[12:13], v[6:7], v[8:9] neg_lo:[0,1] neg_hi:[0,1]
	v_mov_b32_e32 v11, v6
	v_pk_add_f32 v[6:7], v[12:13], v[10:11] neg_lo:[0,1] neg_hi:[0,1]
	v_cmp_nlt_f32_e64 s[0:1], 1.0, v22
	v_add_f32_e32 v7, v18, v7
	v_add_f32_e32 v6, v6, v7
	v_add_f32_e32 v7, v9, v6
	v_mul_f32_e32 v18, v17, v7
	v_mul_f32_e32 v8, v15, v18
	v_fma_f32 v10, v18, v15, -v8
	v_fmac_f32_e32 v10, v18, v16
	v_sub_f32_e32 v9, v9, v7
	v_add_f32_e32 v15, v6, v9
	v_add_f32_e32 v6, v8, v10
	v_sub_f32_e32 v9, v7, v6
	v_pk_add_f32 v[12:13], v[6:7], v[8:9] neg_lo:[0,1] neg_hi:[0,1]
	v_mov_b32_e32 v11, v6
	v_pk_add_f32 v[6:7], v[12:13], v[10:11] neg_lo:[0,1] neg_hi:[0,1]
	s_lshl_b32 s10, s10, 8
	v_add_f32_e32 v7, v15, v7
	v_add_f32_e32 v6, v6, v7
	v_add_f32_e32 v7, v19, v18
	v_add_f32_e32 v6, v9, v6
	v_sub_f32_e32 v8, v7, v19
	v_mul_f32_e32 v6, v17, v6
	v_sub_f32_e32 v8, v18, v8
	v_add_f32_e32 v8, v8, v6
	v_add_f32_e32 v10, v7, v8
	v_mul_f32_e32 v11, v10, v10
	v_fmamk_f32 v6, v11, 0x3e9b6dac, v161
	v_fmaak_f32 v83, v11, v6, 0x3f2aaada
	v_cvt_f32_i32_e32 v6, v14
	v_sub_f32_e32 v7, v10, v7
	v_sub_f32_e32 v7, v8, v7
	v_ldexp_f32 v12, v7, 1
; #define LAS __attribute__((address_space(3)))
; DI float ret_lg2(const Params& p, int l, int dir, int h) { return log1pf(-exp2f(p.in[12][(l * 2 + dir) * 5 + h])) * 1.4426950408889634f; }
; DI void phase_ret_scan(const Params& p, int l, LAS unsigned char* lds) {
;     ...
;         const float lg = ret_lg2(p, l, dir, h), gL = exp2f(lg * 128.f);
;         float wt[4][8];
; #pragma unroll
;         for (int ks = 0; ks < 4; ++ks)
; #pragma unroll
;             for (int e = 0; e < 8; ++e) { const int pp = ks * 32 + q4 * 8 + e; wt[ks][e] = exp2f(lg * (float)(dir == 0 ? 127 - pp : pp)); }
;         const bf16_t* kt = (const bf16_t*)(ws + WS_KTR) + ((size_t)b * 640 + h * 128 + dkb * 16 + r16) * RB + q4 * 8;
;         const LAS unsigned char* vl = lds + r16 * VRS + q4 * 16;
;         bf16_t* sb = (bf16_t*)(ws + WS_S) + ((size_t)((b * 5 + h) * 2 + dir) * 18) * 16384 + (dvb * 16 + r16) * 128 + dkb * 16 + q4 * 4;
;         f32x4 st = (f32x4){0.f, 0.f, 0.f, 0.f};
;         bf16x8 ca[4];
;         { const int c0 = dir == 0 ? 0 : 1;
; #pragma unroll
;           for (int ks = 0; ks < 4; ++ks) ca[ks] = *(const bf16x8*)(kt + c0 * 128 + ks * 32); }
	v_mul_f32_e32 v7, v10, v11
	v_ldexp_f32 v9, v10, 1
	v_pk_mul_f32 v[10:11], v[6:7], v[82:83]
	v_lshl_add_u64 v[4:5], v[84:85], 0, s[10:11]
	v_fma_f32 v8, v6, s15, -v10
	v_fmac_f32_e32 v8, 0xb102e308, v6
	v_pk_add_f32 v[6:7], v[10:11], v[8:9]
	global_load_dwordx4 v[0:3], v[4:5], off
	v_sub_f32_e32 v9, v7, v9
	v_sub_f32_e32 v9, v11, v9
	v_add_f32_e32 v13, v12, v9
	v_mov_b32_e32 v12, v10
	v_pk_add_f32 v[10:11], v[6:7], v[10:11] neg_lo:[0,1] neg_hi:[0,1]
	v_pk_add_f32 v[14:15], v[6:7], v[12:13]
	v_mov_b32_e32 v9, v6
	v_mov_b32_e32 v11, v15
	v_pk_add_f32 v[16:17], v[8:9], v[10:11] neg_lo:[0,1] neg_hi:[0,1]
	v_pk_add_f32 v[8:9], v[8:9], v[10:11]
	v_mov_b32_e32 v20, v7
	v_pk_add_f32 v[10:11], v[8:9], v[6:7] op_sel:[1,0] op_sel_hi:[0,1] neg_lo:[0,1] neg_hi:[0,1]
	v_pk_add_f32 v[18:19], v[14:15], v[10:11] op_sel_hi:[1,0] neg_lo:[0,1] neg_hi:[0,1]
	v_mov_b32_e32 v14, v15
	v_mov_b32_e32 v15, v9
	v_mov_b32_e32 v21, v10
	v_pk_add_f32 v[10:11], v[14:15], v[20:21] neg_lo:[0,1] neg_hi:[0,1]
	v_mov_b32_e32 v12, v13
	v_mov_b32_e32 v13, v6
	v_pk_add_f32 v[6:7], v[12:13], v[10:11] neg_lo:[0,1] neg_hi:[0,1]
	v_mov_b32_e32 v18, v16
	v_pk_add_f32 v[10:11], v[18:19], v[6:7]
	v_mov_b32_e32 v17, v9
	v_pk_add_f32 v[12:13], v[10:11], v[10:11] op_sel:[0,1] op_sel_hi:[1,0]
	v_mov_b32_e32 v81, v41
	v_pk_add_f32 v[8:9], v[8:9], v[12:13] op_sel:[1,0] op_sel_hi:[0,1]
	v_mov_b32_e32 v11, v8
	v_pk_add_f32 v[14:15], v[10:11], v[16:17] neg_lo:[0,1] neg_hi:[0,1]
	v_mov_b32_e32 v7, v12
	v_sub_f32_e32 v9, v10, v14
	v_pk_add_f32 v[6:7], v[6:7], v[14:15] neg_lo:[0,1] neg_hi:[0,1]
	v_sub_f32_e32 v9, v16, v9
	v_add_f32_e32 v6, v6, v9
	v_add_f32_e32 v6, v6, v7
	v_add_f32_e32 v6, v8, v6
	v_cndmask_b32_e64 v6, v163, v6, s[0:1]
	v_cmp_neq_f32_e64 s[0:1], 1.0, v22
	s_mov_b32 s10, 0
	s_nop 0
	v_cndmask_b32_e64 v6, v164, v6, s[0:1]
	v_cmp_lt_f32_e64 s[0:1], |v22|, s16
	s_nop 1
	v_cndmask_b32_e64 v6, v6, -v22, s[0:1]
	v_mul_f32_e32 v18, 0x3fb8aa3b, v6
	v_cndmask_b32_e32 v6, v87, v89, vcc
	v_cvt_f32_ubyte0_e32 v6, v6
	v_mul_f32_e32 v7, v18, v6
	v_cmp_gt_f32_e64 s[0:1], s5, v7
	v_mul_f32_e32 v19, 0x43000000, v18
	v_mov_b32_e32 v22, 0
	v_cndmask_b32_e64 v7, 0, v162, s[0:1]
	v_fmac_f32_e32 v7, v18, v6
	v_exp_f32_e32 v6, v7
	v_cndmask_b32_e64 v7, 0, v165, s[0:1]
	v_mov_b32_e32 v23, v22
	v_mov_b32_e32 v24, v22
	v_ldexp_f32 v26, v6, v7
	v_cndmask_b32_e32 v6, v90, v91, vcc
	v_cvt_f32_ubyte0_e32 v6, v6
	v_mul_f32_e32 v7, v18, v6
	v_cmp_gt_f32_e64 s[0:1], s5, v7
	v_mov_b32_e32 v25, v22
	s_nop 0
	v_cndmask_b32_e64 v7, 0, v162, s[0:1]
	v_fmac_f32_e32 v7, v18, v6
	v_exp_f32_e32 v6, v7
	v_cndmask_b32_e32 v7, v92, v93, vcc
	v_cvt_f32_ubyte0_e32 v7, v7
	v_mul_f32_e32 v8, v18, v7
	v_cmp_gt_f32_e64 s[6:7], s5, v8
	s_nop 1
	v_cndmask_b32_e64 v8, 0, v162, s[6:7]
	v_fmac_f32_e32 v8, v18, v7
	v_exp_f32_e32 v7, v8
	v_cndmask_b32_e64 v8, 0, v165, s[0:1]
	v_ldexp_f32 v27, v6, v8
	v_cndmask_b32_e64 v6, 0, v165, s[6:7]
	v_ldexp_f32 v28, v7, v6
	v_cndmask_b32_e32 v6, v94, v95, vcc
	v_cvt_f32_ubyte0_e32 v6, v6
	v_mul_f32_e32 v7, v18, v6
	v_cmp_gt_f32_e64 s[0:1], s5, v7
	s_nop 1
	v_cndmask_b32_e64 v7, 0, v162, s[0:1]
	v_fmac_f32_e32 v7, v18, v6
	v_exp_f32_e32 v6, v7
	v_cndmask_b32_e32 v7, v96, v97, vcc
	v_cvt_f32_ubyte0_e32 v7, v7
	v_mul_f32_e32 v8, v18, v7
	v_cmp_gt_f32_e64 s[6:7], s5, v8
	s_nop 1
	v_cndmask_b32_e64 v8, 0, v162, s[6:7]
	v_fmac_f32_e32 v8, v18, v7
	v_exp_f32_e32 v7, v8
	v_cndmask_b32_e64 v8, 0, v165, s[0:1]
	v_ldexp_f32 v29, v6, v8
	v_cndmask_b32_e64 v6, 0, v165, s[6:7]
	v_ldexp_f32 v30, v7, v6
	v_cndmask_b32_e32 v6, v98, v99, vcc
	v_cvt_f32_ubyte0_e32 v6, v6
	v_mul_f32_e32 v7, v18, v6
	v_cmp_gt_f32_e64 s[0:1], s5, v7
	s_nop 1
	v_cndmask_b32_e64 v7, 0, v162, s[0:1]
	v_fmac_f32_e32 v7, v18, v6
	v_exp_f32_e32 v6, v7
	v_cndmask_b32_e32 v7, v100, v101, vcc
	v_cvt_f32_ubyte0_e32 v7, v7
	v_mul_f32_e32 v8, v18, v7
	v_cmp_gt_f32_e64 s[6:7], s5, v8
	s_nop 1
	v_cndmask_b32_e64 v8, 0, v162, s[6:7]
	v_fmac_f32_e32 v8, v18, v7
	v_exp_f32_e32 v7, v8
	v_cndmask_b32_e64 v8, 0, v165, s[0:1]
	v_ldexp_f32 v31, v6, v8
	v_cndmask_b32_e64 v6, 0, v165, s[6:7]
	v_ldexp_f32 v32, v7, v6
	v_cndmask_b32_e32 v6, v102, v103, vcc
	v_cvt_f32_ubyte0_e32 v6, v6
	v_mul_f32_e32 v7, v18, v6
	v_cmp_gt_f32_e64 s[0:1], s5, v7
	s_nop 1
	v_cndmask_b32_e64 v7, 0, v162, s[0:1]
	v_fmac_f32_e32 v7, v18, v6
	v_exp_f32_e32 v6, v7
	v_cndmask_b32_e32 v7, v104, v105, vcc
	v_cvt_f32_ubyte0_e32 v7, v7
	v_mul_f32_e32 v8, v18, v7
	v_cmp_gt_f32_e64 s[6:7], s5, v8
	s_nop 1
	v_cndmask_b32_e64 v8, 0, v162, s[6:7]
	v_fmac_f32_e32 v8, v18, v7
	v_exp_f32_e32 v7, v8
	v_cndmask_b32_e64 v8, 0, v165, s[0:1]
	v_ldexp_f32 v33, v6, v8
	v_cndmask_b32_e64 v6, 0, v165, s[6:7]
	v_ldexp_f32 v34, v7, v6
	v_cndmask_b32_e32 v6, v106, v107, vcc
	v_cvt_f32_ubyte0_e32 v6, v6
	v_mul_f32_e32 v7, v18, v6
	v_cmp_gt_f32_e64 s[0:1], s5, v7
	s_nop 1
	v_cndmask_b32_e64 v7, 0, v162, s[0:1]
	v_fmac_f32_e32 v7, v18, v6
	v_exp_f32_e32 v6, v7
	v_cndmask_b32_e32 v7, v108, v109, vcc
	v_cvt_f32_ubyte0_e32 v7, v7
	v_mul_f32_e32 v8, v18, v7
	v_cmp_gt_f32_e64 s[6:7], s5, v8
	s_nop 1
	v_cndmask_b32_e64 v8, 0, v162, s[6:7]
	v_fmac_f32_e32 v8, v18, v7
	v_exp_f32_e32 v7, v8
	v_cndmask_b32_e64 v8, 0, v165, s[0:1]
	v_ldexp_f32 v35, v6, v8
	v_cndmask_b32_e64 v6, 0, v165, s[6:7]
	v_ldexp_f32 v83, v7, v6
	v_cndmask_b32_e32 v6, v110, v111, vcc
	v_cvt_f32_ubyte0_e32 v6, v6
	v_mul_f32_e32 v7, v18, v6
	v_cmp_gt_f32_e64 s[0:1], s5, v7
	s_nop 1
	v_cndmask_b32_e64 v7, 0, v162, s[0:1]
	v_fmac_f32_e32 v7, v18, v6
	v_exp_f32_e32 v6, v7
	v_cndmask_b32_e32 v7, v112, v113, vcc
	v_cvt_f32_ubyte0_e32 v7, v7
	v_mul_f32_e32 v8, v18, v7
	v_cmp_gt_f32_e64 s[6:7], s5, v8
	s_nop 1
	v_cndmask_b32_e64 v8, 0, v162, s[6:7]
; #define LAS __attribute__((address_space(3)))
; DI void phase_ret_scan(const Params& p, int l, LAS unsigned char* lds) {
;     ...
;         for (int ks = 0; ks < 4; ++ks)
; #pragma unroll
;             for (int e = 0; e < 8; ++e) { const int pp = ks * 32 + q4 * 8 + e; wt[ks][e] = exp2f(lg * (float)(dir == 0 ? 127 - pp : pp)); }
;         const bf16_t* kt = (const bf16_t*)(ws + WS_KTR) + ((size_t)b * 640 + h * 128 + dkb * 16 + r16) * RB + q4 * 8;
;         const LAS unsigned char* vl = lds + r16 * VRS + q4 * 16;
;         bf16_t* sb = (bf16_t*)(ws + WS_S) + ((size_t)((b * 5 + h) * 2 + dir) * 18) * 16384 + (dvb * 16 + r16) * 128 + dkb * 16 + q4 * 4;
;         f32x4 st = (f32x4){0.f, 0.f, 0.f, 0.f};
;         bf16x8 ca[4];
;         { const int c0 = dir == 0 ? 0 : 1;
; #pragma unroll
;           for (int ks = 0; ks < 4; ++ks) ca[ks] = *(const bf16x8*)(kt + c0 * 128 + ks * 32); }
;         __syncthreads();
; #pragma unroll 2
;         for (int step = 0; step < 18; ++step) {
;             const int c = dir == 0 ? step : (step < 2 ? 1 - step : 19 - step);
;             const int sn = step < 17 ? step + 1 : 17;
;             const int cn = dir == 0 ? sn : (sn < 2 ? 1 - sn : 19 - sn);
;             bf16x8 na_[4];
; #pragma unroll
;             for (int ks = 0; ks < 4; ++ks) na_[ks] = *(const bf16x8*)(kt + cn * 128 + ks * 32);
	v_fmac_f32_e32 v8, v18, v7
	v_exp_f32_e32 v7, v8
	v_cndmask_b32_e64 v8, 0, v165, s[0:1]
	v_ldexp_f32 v166, v6, v8
	v_cndmask_b32_e64 v6, 0, v165, s[6:7]
	v_ldexp_f32 v167, v7, v6
	v_cndmask_b32_e32 v6, v114, v115, vcc
	v_cvt_f32_ubyte0_e32 v6, v6
	v_mul_f32_e32 v7, v18, v6
	v_cmp_gt_f32_e64 s[0:1], s5, v7
	s_nop 1
	v_cndmask_b32_e64 v7, 0, v162, s[0:1]
	v_fmac_f32_e32 v7, v18, v6
	v_exp_f32_e32 v6, v7
	v_cndmask_b32_e32 v7, v116, v117, vcc
	v_cvt_f32_ubyte0_e32 v7, v7
	v_mul_f32_e32 v8, v18, v7
	v_cmp_gt_f32_e64 s[6:7], s5, v8
	s_nop 1
	v_cndmask_b32_e64 v8, 0, v162, s[6:7]
	v_fmac_f32_e32 v8, v18, v7
	v_exp_f32_e32 v7, v8
	v_cndmask_b32_e64 v8, 0, v165, s[0:1]
	v_ldexp_f32 v168, v6, v8
	v_cndmask_b32_e64 v6, 0, v165, s[6:7]
	v_ldexp_f32 v169, v7, v6
	v_cndmask_b32_e32 v6, v118, v119, vcc
	v_cvt_f32_ubyte0_e32 v6, v6
	v_mul_f32_e32 v7, v18, v6
	v_cmp_gt_f32_e64 s[0:1], s5, v7
	s_nop 1
	v_cndmask_b32_e64 v7, 0, v162, s[0:1]
	v_fmac_f32_e32 v7, v18, v6
	v_exp_f32_e32 v6, v7
	v_cndmask_b32_e32 v7, v120, v121, vcc
	v_cvt_f32_ubyte0_e32 v7, v7
	v_mul_f32_e32 v8, v18, v7
	v_cmp_gt_f32_e64 s[6:7], s5, v8
	s_nop 1
	v_cndmask_b32_e64 v8, 0, v162, s[6:7]
	v_fmac_f32_e32 v8, v18, v7
	v_exp_f32_e32 v7, v8
	v_cndmask_b32_e64 v8, 0, v165, s[0:1]
	v_ldexp_f32 v170, v6, v8
	v_cndmask_b32_e64 v6, 0, v165, s[6:7]
	v_ldexp_f32 v171, v7, v6
	v_cndmask_b32_e32 v6, v122, v123, vcc
	v_cvt_f32_ubyte0_e32 v6, v6
	v_mul_f32_e32 v7, v18, v6
	v_cmp_gt_f32_e64 s[0:1], s5, v7
	s_nop 1
	v_cndmask_b32_e64 v7, 0, v162, s[0:1]
	v_fmac_f32_e32 v7, v18, v6
	v_exp_f32_e32 v6, v7
	v_cndmask_b32_e32 v7, v124, v125, vcc
	v_cvt_f32_ubyte0_e32 v7, v7
	v_mul_f32_e32 v8, v18, v7
	v_cmp_gt_f32_e64 s[6:7], s5, v8
	s_nop 1
	v_cndmask_b32_e64 v8, 0, v162, s[6:7]
	v_fmac_f32_e32 v8, v18, v7
	v_exp_f32_e32 v7, v8
	v_cndmask_b32_e64 v8, 0, v165, s[0:1]
	v_ldexp_f32 v172, v6, v8
	v_cndmask_b32_e64 v6, 0, v165, s[6:7]
	v_ldexp_f32 v173, v7, v6
	v_cndmask_b32_e32 v6, v126, v127, vcc
	v_cvt_f32_ubyte0_e32 v6, v6
	v_mul_f32_e32 v7, v18, v6
	v_cmp_gt_f32_e64 s[0:1], s5, v7
	s_nop 1
	v_cndmask_b32_e64 v7, 0, v162, s[0:1]
	v_fmac_f32_e32 v7, v18, v6
	v_exp_f32_e32 v6, v7
	v_cndmask_b32_e32 v7, v128, v129, vcc
	v_cvt_f32_ubyte0_e32 v7, v7
	v_mul_f32_e32 v8, v18, v7
	v_cmp_gt_f32_e64 s[6:7], s5, v8
	s_nop 1
	v_cndmask_b32_e64 v8, 0, v162, s[6:7]
	v_fmac_f32_e32 v8, v18, v7
	v_exp_f32_e32 v7, v8
	v_cndmask_b32_e64 v8, 0, v165, s[0:1]
	v_ldexp_f32 v174, v6, v8
	v_cndmask_b32_e64 v6, 0, v165, s[6:7]
	v_ldexp_f32 v175, v7, v6
	v_cndmask_b32_e32 v6, v130, v131, vcc
	v_cvt_f32_ubyte0_e32 v6, v6
	v_mul_f32_e32 v7, v18, v6
	v_cmp_gt_f32_e64 s[0:1], s5, v7
	s_nop 1
	v_cndmask_b32_e64 v7, 0, v162, s[0:1]
	v_fmac_f32_e32 v7, v18, v6
	v_exp_f32_e32 v6, v7
	v_cndmask_b32_e32 v7, v132, v133, vcc
	v_cvt_f32_ubyte0_e32 v7, v7
	v_mul_f32_e32 v8, v18, v7
	v_cmp_gt_f32_e64 s[6:7], s5, v8
	s_nop 1
	v_cndmask_b32_e64 v8, 0, v162, s[6:7]
	v_fmac_f32_e32 v8, v18, v7
	v_exp_f32_e32 v7, v8
	v_cndmask_b32_e64 v8, 0, v165, s[0:1]
	v_ldexp_f32 v176, v6, v8
	v_cndmask_b32_e64 v6, 0, v165, s[6:7]
	v_ldexp_f32 v177, v7, v6
	v_cndmask_b32_e32 v6, v134, v135, vcc
	v_cvt_f32_ubyte0_e32 v6, v6
	v_mul_f32_e32 v7, v18, v6
	v_cmp_gt_f32_e64 s[0:1], s5, v7
	s_nop 1
	v_cndmask_b32_e64 v7, 0, v162, s[0:1]
	v_fmac_f32_e32 v7, v18, v6
	v_exp_f32_e32 v6, v7
	v_cndmask_b32_e32 v7, v136, v137, vcc
	v_cvt_f32_ubyte0_e32 v7, v7
	v_mul_f32_e32 v8, v18, v7
	v_cmp_gt_f32_e64 s[6:7], s5, v8
	s_nop 1
	v_cndmask_b32_e64 v8, 0, v162, s[6:7]
	v_fmac_f32_e32 v8, v18, v7
	v_exp_f32_e32 v7, v8
	v_cndmask_b32_e64 v8, 0, v165, s[0:1]
	v_ldexp_f32 v178, v6, v8
	v_cndmask_b32_e64 v6, 0, v165, s[6:7]
	v_ldexp_f32 v179, v7, v6
	v_cndmask_b32_e32 v6, v138, v139, vcc
	v_cvt_f32_ubyte0_e32 v6, v6
	v_mul_f32_e32 v7, v18, v6
	v_cmp_gt_f32_e64 s[0:1], s5, v7
	s_nop 1
	v_cndmask_b32_e64 v7, 0, v162, s[0:1]
	v_fmac_f32_e32 v7, v18, v6
	v_exp_f32_e32 v16, v7
	global_load_dwordx4 v[12:15], v[4:5], off offset:64
	global_load_dwordx4 v[8:11], v[4:5], off offset:128
	s_nop 0
	global_load_dwordx4 v[4:7], v[4:5], off offset:192
	v_lshlrev_b32_e32 v254, 4, v202
	v_add_u32_e32 v254, 0x14000, v254
	ds_write_b128 v254, v[92:95]
	ds_write_b128 v254, v[96:99] offset:8192
	ds_write_b128 v254, v[100:103] offset:16384
	ds_write_b128 v254, v[104:107] offset:24576
	s_waitcnt lgkmcnt(0)
	s_and_b64 s[100:101], vcc, exec
	s_cselect_b32 s98, 1, 0
	s_lshl_b32 s98, s98, 8
	s_mov_b32 s99, 0
	v_lshl_add_u64 v[250:251], s[98:99], 0, v[84:85]
	global_load_dwordx4 v[92:95], v[250:251], off
	global_load_dwordx4 v[96:99], v[250:251], off offset:64
	global_load_dwordx4 v[100:103], v[250:251], off offset:128
	global_load_dwordx4 v[104:107], v[250:251], off offset:192
	s_and_b64 s[100:101], vcc, exec
	s_cselect_b32 s98, 2, 17
	s_lshl_b32 s98, s98, 8
	v_lshl_add_u64 v[250:251], s[98:99], 0, v[84:85]
	global_load_dwordx4 v[234:237], v[250:251], off
	global_load_dwordx4 v[238:241], v[250:251], off offset:64
	global_load_dwordx4 v[242:245], v[250:251], off offset:128
	global_load_dwordx4 v[246:249], v[250:251], off offset:192
	v_cndmask_b32_e64 v17, 0, v165, s[0:1]
	s_waitcnt lgkmcnt(0)
	v_ldexp_f32 v180, v16, v17
	v_cndmask_b32_e32 v16, v140, v141, vcc
	v_cvt_f32_ubyte0_e32 v16, v16
	v_mul_f32_e32 v17, v18, v16
	v_cmp_gt_f32_e64 s[0:1], s5, v17
	s_barrier
; #define LAS __attribute__((address_space(3)))
; DI void phase_ret_scan(const Params& p, int l, LAS unsigned char* lds) {
;     ...
;         for (int ks = 0; ks < 4; ++ks)
; #pragma unroll
;             for (int e = 0; e < 8; ++e) { const int pp = ks * 32 + q4 * 8 + e; wt[ks][e] = exp2f(lg * (float)(dir == 0 ? 127 - pp : pp)); }
;         const bf16_t* kt = (const bf16_t*)(ws + WS_KTR) + ((size_t)b * 640 + h * 128 + dkb * 16 + r16) * RB + q4 * 8;
;         const LAS unsigned char* vl = lds + r16 * VRS + q4 * 16;
;         bf16_t* sb = (bf16_t*)(ws + WS_S) + ((size_t)((b * 5 + h) * 2 + dir) * 18) * 16384 + (dvb * 16 + r16) * 128 + dkb * 16 + q4 * 4;
;         f32x4 st = (f32x4){0.f, 0.f, 0.f, 0.f};
;         bf16x8 ca[4];
;         { const int c0 = dir == 0 ? 0 : 1;
; #pragma unroll
;           for (int ks = 0; ks < 4; ++ks) ca[ks] = *(const bf16x8*)(kt + c0 * 128 + ks * 32); }
;         __syncthreads();
; #pragma unroll 2
;         for (int step = 0; step < 18; ++step) {
	s_nop 0
	v_cndmask_b32_e64 v17, 0, v162, s[0:1]
	v_fmac_f32_e32 v17, v18, v16
	v_exp_f32_e32 v16, v17
	v_cndmask_b32_e32 v17, v142, v143, vcc
	v_cvt_f32_ubyte0_e32 v17, v17
	v_mul_f32_e32 v20, v18, v17
	v_cmp_gt_f32_e64 s[6:7], s5, v20
	s_nop 1
	v_cndmask_b32_e64 v20, 0, v162, s[6:7]
	v_fmac_f32_e32 v20, v18, v17
	v_exp_f32_e32 v17, v20
	v_cndmask_b32_e64 v20, 0, v165, s[0:1]
	v_ldexp_f32 v181, v16, v20
	v_cndmask_b32_e64 v16, 0, v165, s[6:7]
	v_ldexp_f32 v182, v17, v16
	v_cndmask_b32_e32 v16, v144, v145, vcc
	v_cvt_f32_ubyte0_e32 v16, v16
	v_mul_f32_e32 v17, v18, v16
	v_cmp_gt_f32_e64 s[0:1], s5, v17
	s_nop 1
	v_cndmask_b32_e64 v17, 0, v162, s[0:1]
	v_fmac_f32_e32 v17, v18, v16
	v_exp_f32_e32 v16, v17
	v_cndmask_b32_e32 v17, v146, v147, vcc
	v_cvt_f32_ubyte0_e32 v17, v17
	v_mul_f32_e32 v20, v18, v17
	v_cmp_gt_f32_e64 s[6:7], s5, v20
	s_nop 1
	v_cndmask_b32_e64 v20, 0, v162, s[6:7]
	v_fmac_f32_e32 v20, v18, v17
	v_exp_f32_e32 v17, v20
	v_cndmask_b32_e64 v20, 0, v165, s[0:1]
	v_ldexp_f32 v183, v16, v20
	v_cndmask_b32_e64 v16, 0, v165, s[6:7]
	v_ldexp_f32 v184, v17, v16
	v_cndmask_b32_e32 v16, v148, v149, vcc
	v_cvt_f32_ubyte0_e32 v16, v16
	v_mul_f32_e32 v17, v18, v16
	v_cmp_gt_f32_e64 s[0:1], s5, v17
	s_nop 1
	v_cndmask_b32_e64 v17, 0, v162, s[0:1]
	v_fmac_f32_e32 v17, v18, v16
	v_exp_f32_e32 v16, v17
	v_cndmask_b32_e32 v17, v150, v151, vcc
	v_cvt_f32_ubyte0_e32 v17, v17
	v_mul_f32_e32 v20, v18, v17
	v_cmp_gt_f32_e64 s[6:7], s5, v20
	s_nop 1
	v_cndmask_b32_e64 v20, 0, v162, s[6:7]
	v_fmac_f32_e32 v20, v18, v17
	v_exp_f32_e32 v17, v20
	v_cndmask_b32_e64 v20, 0, v165, s[0:1]
	v_cmp_gt_f32_e64 s[0:1], s5, v19
	v_ldexp_f32 v185, v16, v20
	v_cndmask_b32_e64 v16, 0, v165, s[6:7]
	v_cndmask_b32_e64 v19, 0, v162, s[0:1]
	v_fmac_f32_e32 v19, 0x43000000, v18
	v_exp_f32_e32 v18, v19
	v_ldexp_f32 v186, v17, v16
	v_or_b32_e32 v16, s17, v86
	v_lshlrev_b32_e32 v40, 8, v16
	s_and_b64 s[0:1], s[0:1], exec
	v_lshl_add_u64 v[16:17], s[12:13], 0, v[40:41]
	s_cselect_b32 s0, 0xffffffc0, 0
	v_lshl_add_u64 v[16:17], v[36:37], 1, v[16:17]
	v_ldexp_f32 v18, v18, s0
	v_lshl_add_u64 v[16:17], v[16:17], 0, v[80:81]
	v_mov_b32_e32 v20, v18
	v_mov_b32_e32 v21, v18
	s_mov_b32 s0, 0
	s_waitcnt vmcnt(8)

; #define LAS __attribute__((address_space(3)))
; DI int otid() { int t = threadIdx.x; asm volatile("" : "+v"(t)); return t; }
; DI float ret_lg2(const Params& p, int l, int dir, int h) { return log1pf(-exp2f(p.in[12][(l * 2 + dir) * 5 + h])) * 1.4426950408889634f; }
; DI void phase_ret_scan(const Params& p, int l, LAS unsigned char* lds) {
;     const int tid = otid(), lane = tid & 63, wid = tid >> 6, r16 = lane & 15, q4 = lane >> 4;
;     unsigned char* ws = p.ws;
;     volatile LAS int* slot = (volatile LAS int*)(lds + LDS_CTRL + 64);
;     unsigned* ctr = (unsigned*)(ws + WS_QCTR + 256 * (3 + l));
;     constexpr int VRS = RB * 2 + 16;
;     for (;;) {
;         const int it = next_item(ctr, slot);
;         if (it >= 320) break;
;         const int dvb = it & 7, dir = (it >> 3) & 1, h = (it >> 4) % 5, b = it / 80, dkb = wid;
;         {
;             const bf16_t* vsrc = (const bf16_t*)(ws + WS_VTR) + ((size_t)b * 640 + h * 128 + dvb * 16) * RB;
;             u32x4 t[9];
; #pragma unroll
;             for (int i = 0; i < 9; ++i) { const int cid = tid + i * 512, rr = cid / 288, cc = cid % 288; t[i] = *(const u32x4*)(vsrc + (size_t)rr * RB + cc * 8); }
; #pragma unroll
;             for (int i = 0; i < 9; ++i) { const int cid = tid + i * 512, rr = cid / 288, cc = cid % 288; *(LAS u32x4*)(lds + rr * VRS + cc * 16) = t[i]; }
;         }
;         const float lg = ret_lg2(p, l, dir, h), gL = exp2f(lg * 128.f);
;         float wt[4][8];
; #pragma unroll
;         for (int ks = 0; ks < 4; ++ks)
; #pragma unroll
;             for (int e = 0; e < 8; ++e) { const int pp = ks * 32 + q4 * 8 + e; wt[ks][e] = exp2f(lg * (float)(dir == 0 ? 127 - pp : pp)); }
;         const bf16_t* kt = (const bf16_t*)(ws + WS_KTR) + ((size_t)b * 640 + h * 128 + dkb * 16 + r16) * RB + q4 * 8;
;         const LAS unsigned char* vl = lds + r16 * VRS + q4 * 16;
;         bf16_t* sb = (bf16_t*)(ws + WS_S) + ((size_t)((b * 5 + h) * 2 + dir) * 18) * 16384 + (dvb * 16 + r16) * 128 + dkb * 16 + q4 * 4;
.LBB0_2523:
	v_mov_b32_e32 v1, v202
	v_readlane_b32 s0, v253, 21
	v_bfe_u32 v0, v1, 4, 2
	v_lshlrev_b32_e32 v40, 4, v0
	v_mov_b32_e32 v41, 0
	v_readlane_b32 s1, v253, 22
	v_add_u32_e32 v4, 0x200, v1
	v_and_b32_e32 v86, 15, v1
	v_lshl_add_u64 v[42:43], s[0:1], 0, v[40:41]
	s_mov_b32 s1, 0x38e38e39
	v_mul_hi_i32 v5, v4, s1
	v_lshrrev_b32_e32 v6, 31, v5
	v_ashrrev_i32_e32 v5, 6, v5
	v_add_u32_e32 v5, v5, v6
	v_mul_i32_i24_e32 v6, 0x120, v5
	v_sub_u32_e32 v4, v4, v6
	v_add_u32_e32 v6, 0x400, v1
	v_mul_hi_i32 v7, v6, s1
	v_lshrrev_b32_e32 v8, 31, v7
	v_ashrrev_i32_e32 v7, 6, v7
	v_add_u32_e32 v7, v7, v8
	v_mul_i32_i24_e32 v8, 0x120, v7
	v_sub_u32_e32 v6, v6, v8
	v_add_u32_e32 v8, 0x600, v1
	v_mul_hi_i32 v9, v8, s1
	v_lshrrev_b32_e32 v10, 31, v9
	v_ashrrev_i32_e32 v9, 6, v9
	v_add_u32_e32 v9, v9, v10
	v_mul_i32_i24_e32 v10, 0x120, v9
	v_sub_u32_e32 v8, v8, v10
	v_add_u32_e32 v10, 0x800, v1
	v_mul_hi_i32 v11, v10, s1
	v_lshrrev_b32_e32 v12, 31, v11
	v_ashrrev_i32_e32 v11, 6, v11
	v_add_u32_e32 v11, v11, v12
	v_mul_i32_i24_e32 v12, 0x120, v11
	v_sub_u32_e32 v10, v10, v12
	v_add_u32_e32 v12, 0xa00, v1
	v_mul_hi_i32 v13, v12, s1
	v_lshrrev_b32_e32 v14, 31, v13
	v_ashrrev_i32_e32 v13, 6, v13
	v_add_u32_e32 v13, v13, v14
	v_mul_i32_i24_e32 v14, 0x120, v13
	v_sub_u32_e32 v12, v12, v14
	v_add_u32_e32 v14, 0xc00, v1
	v_mul_hi_i32 v15, v14, s1
	v_lshrrev_b32_e32 v16, 31, v15
	v_ashrrev_i32_e32 v15, 6, v15
	v_ashrrev_i32_e32 v2, 2, v1
	v_add_u32_e32 v15, v15, v16
	v_and_b32_e32 v36, -16, v2
	v_mul_u32_u24_e32 v2, 0x1210, v86
	v_mul_i32_i24_e32 v16, 0x120, v15
	v_add3_u32 v88, 0, v2, v40
	v_mul_hi_i32 v2, v1, s1
	v_sub_u32_e32 v14, v14, v16
	v_add_u32_e32 v16, 0xe00, v1
	v_lshrrev_b32_e32 v3, 31, v2
	v_ashrrev_i32_e32 v2, 6, v2
	v_mul_hi_i32 v17, v16, s1
	v_add_u32_e32 v2, v2, v3
	v_lshrrev_b32_e32 v18, 31, v17
	v_ashrrev_i32_e32 v17, 6, v17
	v_mul_i32_i24_e32 v3, 0x120, v2
	v_add_u32_e32 v17, v17, v18
	v_sub_u32_e32 v3, v1, v3
	v_mul_i32_i24_e32 v18, 0x120, v17
	v_add_u32_e32 v1, 0x1000, v1
	v_sub_u32_e32 v16, v16, v18
	v_mul_hi_i32 v18, v1, s1
	v_lshrrev_b32_e32 v19, 31, v18
	v_ashrrev_i32_e32 v18, 6, v18
	v_add_u32_e32 v18, v18, v19
	v_mul_i32_i24_e32 v19, 0x120, v18
	s_movk_i32 s0, 0x1210
	v_sub_u32_e32 v1, v1, v19
	s_and_b32 s4, s26, 7
	s_lshl_b32 s4, s4, 8
	s_add_u32 s4, s4, 0x5000
	s_cmp_eq_u32 s33, 0x100
	s_cselect_b32 s4, s4, 0x4400
	s_add_u32 s4, s50, s4
	v_lshlrev_b32_e32 v87, 3, v0
	v_ashrrev_i32_e32 v37, 31, v36
	v_lshlrev_b32_e32 v0, 2, v0
	v_mul_hi_i32_i24_e32 v45, 0x1200, v2
	v_mul_i32_i24_e32 v44, 0x1200, v2
	v_lshlrev_b32_e32 v46, 3, v3
	v_mul_hi_i32_i24_e32 v49, 0x1200, v5
	v_mul_i32_i24_e32 v48, 0x1200, v5
	v_lshlrev_b32_e32 v50, 3, v4
	v_mul_hi_i32_i24_e32 v53, 0x1200, v7
	v_mul_i32_i24_e32 v52, 0x1200, v7
	v_lshlrev_b32_e32 v54, 3, v6
	v_mul_hi_i32_i24_e32 v57, 0x1200, v9
	v_mul_i32_i24_e32 v56, 0x1200, v9
	v_lshlrev_b32_e32 v58, 3, v8
	v_mul_hi_i32_i24_e32 v61, 0x1200, v11
	v_mul_i32_i24_e32 v60, 0x1200, v11
	v_lshlrev_b32_e32 v62, 3, v10
	v_mul_hi_i32_i24_e32 v65, 0x1200, v13
	v_mul_i32_i24_e32 v64, 0x1200, v13
	v_lshlrev_b32_e32 v66, 3, v12
	v_mul_hi_i32_i24_e32 v69, 0x1200, v15
	v_mul_i32_i24_e32 v68, 0x1200, v15
	v_lshlrev_b32_e32 v70, 3, v14
	v_mul_hi_i32_i24_e32 v73, 0x1200, v17
	v_mul_i32_i24_e32 v72, 0x1200, v17
	v_lshlrev_b32_e32 v74, 3, v16
	v_mul_hi_i32_i24_e32 v77, 0x1200, v18
	v_mul_i32_i24_e32 v76, 0x1200, v18
	v_lshlrev_b32_e32 v78, 3, v1
	v_mad_i32_i24 v2, v2, s0, 0
	v_lshlrev_b32_e32 v3, 4, v3
	v_mad_i32_i24 v5, v5, s0, 0
	v_lshlrev_b32_e32 v4, 4, v4
	v_mad_i32_i24 v7, v7, s0, 0
	v_lshlrev_b32_e32 v6, 4, v6
	v_mad_i32_i24 v9, v9, s0, 0
	v_lshlrev_b32_e32 v8, 4, v8
	v_mad_i32_i24 v11, v11, s0, 0
	v_lshlrev_b32_e32 v10, 4, v10
	v_mad_i32_i24 v13, v13, s0, 0
	v_lshlrev_b32_e32 v12, 4, v12
	v_mad_i32_i24 v15, v15, s0, 0
	v_lshlrev_b32_e32 v14, 4, v14
	v_mad_i32_i24 v17, v17, s0, 0
	v_lshlrev_b32_e32 v16, 4, v16
	v_mad_i32_i24 v18, v18, s0, 0
	v_lshlrev_b32_e32 v1, 4, v1
	s_addc_u32 s5, s51, 0
	v_or_b32_e32 v38, v36, v86
	v_mov_b32_e32 v39, v37
	s_mov_b32 s9, 0
	s_movk_i32 s6, 0x1200
	v_ashrrev_i32_e32 v47, 31, v46
	v_ashrrev_i32_e32 v51, 31, v50
	v_ashrrev_i32_e32 v55, 31, v54
	v_ashrrev_i32_e32 v59, 31, v58
	v_ashrrev_i32_e32 v63, 31, v62
	v_ashrrev_i32_e32 v67, 31, v66
	v_ashrrev_i32_e32 v71, 31, v70
	v_ashrrev_i32_e32 v75, 31, v74
	v_ashrrev_i32_e32 v79, 31, v78
	v_xor_b32_e32 v89, 0x7f, v87
	v_or_b32_e32 v90, 1, v87
	v_xor_b32_e32 v91, 0x7e, v87
	v_or_b32_e32 v92, 2, v87
	v_xor_b32_e32 v93, 0x7d, v87
	v_or_b32_e32 v94, 3, v87
	v_xor_b32_e32 v95, 0x7c, v87
	v_or_b32_e32 v96, 4, v87
	v_xor_b32_e32 v97, 0x7b, v87
	v_or_b32_e32 v98, 5, v87
	v_xor_b32_e32 v99, 0x7a, v87
	v_or_b32_e32 v100, 6, v87
	v_xor_b32_e32 v101, 0x79, v87
	v_or_b32_e32 v102, 7, v87
	v_xor_b32_e32 v103, 0x78, v87
	v_or_b32_e32 v104, 32, v87
	v_xor_b32_e32 v105, 0x5f, v87
	v_or_b32_e32 v106, 33, v87
	v_xor_b32_e32 v107, 0x5e, v87
	v_or_b32_e32 v108, 34, v87
	v_xor_b32_e32 v109, 0x5d, v87
	v_or_b32_e32 v110, 35, v87
	v_xor_b32_e32 v111, 0x5c, v87
	v_or_b32_e32 v112, 36, v87
	v_xor_b32_e32 v113, 0x5b, v87
	v_or_b32_e32 v114, 37, v87
	v_xor_b32_e32 v115, 0x5a, v87
	v_or_b32_e32 v116, 38, v87
	v_xor_b32_e32 v117, 0x59, v87
	v_or_b32_e32 v118, 39, v87
	v_xor_b32_e32 v119, 0x58, v87
	v_or_b32_e32 v120, 64, v87
	v_xor_b32_e32 v121, 63, v87
	v_or_b32_e32 v122, 0x41, v87
	v_xor_b32_e32 v123, 62, v87
	v_or_b32_e32 v124, 0x42, v87
	v_xor_b32_e32 v125, 61, v87
	v_or_b32_e32 v126, 0x43, v87
	v_xor_b32_e32 v127, 60, v87
	v_or_b32_e32 v128, 0x44, v87
	v_xor_b32_e32 v129, 59, v87
	v_or_b32_e32 v130, 0x45, v87
	v_xor_b32_e32 v131, 58, v87
	v_or_b32_e32 v132, 0x46, v87
	v_xor_b32_e32 v133, 57, v87
	v_or_b32_e32 v134, 0x47, v87
	v_xor_b32_e32 v135, 56, v87
	v_or_b32_e32 v136, 0x60, v87
	v_xor_b32_e32 v137, 31, v87
	v_or_b32_e32 v138, 0x61, v87
	v_xor_b32_e32 v139, 30, v87
	v_or_b32_e32 v140, 0x62, v87
	v_xor_b32_e32 v141, 29, v87
	v_or_b32_e32 v142, 0x63, v87
	v_xor_b32_e32 v143, 28, v87
	v_or_b32_e32 v144, 0x64, v87
	v_xor_b32_e32 v145, 27, v87
	v_or_b32_e32 v146, 0x65, v87
	v_xor_b32_e32 v147, 26, v87
	v_or_b32_e32 v148, 0x66, v87
	v_xor_b32_e32 v149, 25, v87
	v_or_b32_e32 v150, 0x67, v87
	v_xor_b32_e32 v151, 24, v87
	s_add_i32 s7, 0, 0x22040
	s_cmp_eq_u32 s33, 0x100
	s_cselect_b32 s12, 39, 0x13f
	v_add_u32_e32 v152, v2, v3
	v_add_u32_e32 v153, v5, v4
	v_add_u32_e32 v154, v7, v6
	v_add_u32_e32 v155, v9, v8
	v_add_u32_e32 v156, v11, v10
	v_add_u32_e32 v157, v13, v12
	v_add_u32_e32 v158, v15, v14
	v_add_u32_e32 v159, v17, v16
	v_add_u32_e32 v160, v18, v1
	s_mov_b32 s13, 0xc2fc0000
	s_mov_b32 s14, 0x3f2aaaab
	v_mov_b32_e32 v161, 0x3ecc95a3
	s_mov_b32 s15, 0x3f317218
	s_mov_b32 s16, 0x33800000
	v_lshlrev_b32_e32 v80, 1, v0
	v_mov_b32_e32 v162, 0x42800000
	v_mov_b32_e32 v82, 0x3f317218
	v_mov_b32_e32 v163, 0x7fc00000
	v_mov_b32_e32 v164, 0xff800000
	v_not_b32_e32 v165, 63
	s_branch .LBB0_2525

; #define LAS __attribute__((address_space(3)))
; DI unsigned xb_add(unsigned* p, unsigned v) { return __hip_atomic_fetch_add(p, v, __ATOMIC_RELAXED, __HIP_MEMORY_SCOPE_AGENT); }
; DI float ret_lg2(const Params& p, int l, int dir, int h) { return log1pf(-exp2f(p.in[12][(l * 2 + dir) * 5 + h])) * 1.4426950408889634f; }
; DI int next_item(unsigned* ctr, volatile LAS int* slot) {
;     __syncthreads();
;     if (threadIdx.x == 0) *slot = (int)xb_add(ctr, 1u);
;     __syncthreads();
;     return *slot;
; DI void phase_ret_scan(const Params& p, int l, LAS unsigned char* lds) {
;     ...
;     for (;;) {
;         const int it = next_item(ctr, slot);
;         if (it >= 320) break;
;         const int dvb = it & 7, dir = (it >> 3) & 1, h = (it >> 4) % 5, b = it / 80, dkb = wid;
;         {
;             const bf16_t* vsrc = (const bf16_t*)(ws + WS_VTR) + ((size_t)b * 640 + h * 128 + dvb * 16) * RB;
;             u32x4 t[9];
; #pragma unroll
;             for (int i = 0; i < 9; ++i) { const int cid = tid + i * 512, rr = cid / 288, cc = cid % 288; t[i] = *(const u32x4*)(vsrc + (size_t)rr * RB + cc * 8); }
; #pragma unroll
;             for (int i = 0; i < 9; ++i) { const int cid = tid + i * 512, rr = cid / 288, cc = cid % 288; *(LAS u32x4*)(lds + rr * VRS + cc * 16) = t[i]; }
;         }
;         const float lg = ret_lg2(p, l, dir, h), gL = exp2f(lg * 128.f);
.LBB0_2529:
	s_or_b64 exec, exec, s[0:1]
	s_waitcnt vmcnt(0)
	v_mov_b32_e32 v0, s7
	s_waitcnt lgkmcnt(0)
	s_barrier
	ds_read_b32 v0, v0
	s_mov_b64 s[0:1], -1
	s_waitcnt lgkmcnt(0)
	v_cmp_lt_i32_e32 vcc, s12, v0
	v_readfirstlane_b32 s8, v0
	s_cbranch_vccnz .LBB0_2524
	s_cmp_lg_u32 s33, 0x100
	s_cbranch_scc1 sx1_k
	s_and_b32 s0, s26, 7
	s_lshl_b32 s0, s0, 3
	s_lshr_b32 s1, s8, 3
	s_lshl_b32 s1, s1, 6
	s_and_b32 s8, s8, 7
	s_add_u32 s8, s8, s0
	s_add_u32 s8, s8, s1
sx1_k:
	s_ashr_i32 s0, s8, 4
	s_mul_hi_i32 s1, s0, 0x66666667
	s_lshr_b32 s2, s1, 31
	s_ashr_i32 s1, s1, 1
	s_add_i32 s1, s1, s2
	s_mul_i32 s1, s1, 5
	s_sub_i32 s2, s0, s1
	s_mul_hi_i32 s0, s8, 0x66666667
	s_lshr_b32 s1, s0, 31
	s_ashr_i32 s3, s0, 5
	s_add_i32 s3, s3, s1
	s_lshl_b32 s10, s2, 7
	s_mul_i32 s0, s3, 0x280
	s_ashr_i32 s11, s10, 31
	s_mul_hi_i32 s1, s3, 0x280
	s_add_u32 s0, s0, s10
	s_addc_u32 s1, s1, s11
	s_lshl_b32 s10, s8, 4
	s_and_b32 s17, s10, 0x70
	s_or_b32 s10, s0, s17
	s_mul_i32 s11, s1, 0x1200
	s_mul_hi_u32 s18, s10, 0x1200
	s_add_i32 s18, s18, s11
	s_mulk_i32 s10, 0x1200
	s_add_u32 s10, s87, s10
	s_addc_u32 s11, s91, s18
	s_bfe_u32 s18, s8, 0x10003
	v_lshl_add_u64 v[0:1], s[10:11], 0, v[44:45]
	v_lshl_add_u64 v[2:3], s[10:11], 0, v[48:49]
	v_lshl_add_u64 v[8:9], s[10:11], 0, v[52:53]
	s_mul_i32 s8, s18, 5
	v_lshl_add_u64 v[0:1], v[46:47], 1, v[0:1]
	v_lshl_add_u64 v[4:5], v[50:51], 1, v[2:3]
	v_lshl_add_u64 v[8:9], v[54:55], 1, v[8:9]
	v_lshl_add_u64 v[10:11], s[10:11], 0, v[56:57]
	s_add_i32 s8, s2, s8
	global_load_dwordx4 v[0:3], v[0:1], off
	s_nop 0
	global_load_dwordx4 v[4:7], v[4:5], off
	v_lshl_add_u64 v[10:11], v[58:59], 1, v[10:11]
	global_load_dwordx4 v[12:15], v[8:9], off
	global_load_dwordx4 v[16:19], v[10:11], off
	v_lshl_add_u64 v[8:9], s[10:11], 0, v[60:61]
	s_add_i32 s8, s8, 10
	v_lshl_add_u64 v[8:9], v[62:63], 1, v[8:9]
	v_lshl_add_u64 v[10:11], s[10:11], 0, v[64:65]
	s_lshl_b64 s[20:21], s[8:9], 2
	v_lshl_add_u64 v[10:11], v[66:67], 1, v[10:11]
	global_load_dwordx4 v[20:23], v[8:9], off
	global_load_dwordx4 v[24:27], v[10:11], off
	v_lshl_add_u64 v[8:9], s[10:11], 0, v[68:69]
	s_add_u32 s20, s60, s20
	v_lshl_add_u64 v[8:9], v[70:71], 1, v[8:9]
	v_lshl_add_u64 v[10:11], s[10:11], 0, v[72:73]
	s_addc_u32 s21, s61, s21
	v_lshl_add_u64 v[10:11], v[74:75], 1, v[10:11]
	global_load_dwordx4 v[28:31], v[8:9], off
	global_load_dwordx4 v[32:35], v[10:11], off
	global_load_dword v81, v41, s[20:21]
	v_lshl_add_u64 v[8:9], s[10:11], 0, v[76:77]
	v_lshl_add_u64 v[8:9], v[78:79], 1, v[8:9]
	global_load_dwordx4 v[8:11], v[8:9], off
	v_lshl_add_u64 v[166:167], v[38:39], 0, s[0:1]
	v_mad_u64_u32 v[84:85], s[0:1], v166, s6, v[42:43]
	v_mov_b32_e32 v40, v85
	v_mad_u64_u32 v[166:167], s[0:1], v167, s6, v[40:41]
	s_mul_i32 s3, s3, 5
	v_mov_b32_e32 v85, v166
	s_waitcnt vmcnt(0)
	ds_write_b128 v152, v[0:3]
	ds_write_b128 v153, v[4:7]
	ds_write_b128 v154, v[12:15]
	ds_write_b128 v155, v[16:19]
	ds_write_b128 v156, v[20:23]
	ds_write_b128 v157, v[24:27]
	ds_write_b128 v158, v[28:31]
	ds_write_b128 v159, v[32:35]
	v_cmp_gt_f32_e32 vcc, s13, v81
	s_and_b64 s[0:1], vcc, exec
	s_cselect_b32 s0, 0xffffffc0, 0
	v_cndmask_b32_e32 v0, 0, v162, vcc
	v_add_f32_e32 v0, v81, v0
	v_exp_f32_e32 v0, v0
	s_cmp_eq_u32 s18, 0
	s_cselect_b64 vcc, -1, 0
	s_add_i32 s3, s3, s2
	s_lshl_b32 s1, s3, 1
	s_or_b32 s1, s1, s18
	v_ldexp_f32 v22, v0, s0
	s_mul_hi_i32 s0, s1, 0x90000
	s_mul_i32 s1, s1, 0x90000
	v_sub_f32_e32 v6, 1.0, v22
	s_add_u32 s10, s92, s1
	v_add_f32_e32 v2, -1.0, v6
	v_frexp_mant_f32_e32 v7, v6
	v_cvt_f64_f32_e32 v[0:1], v6
	s_addc_u32 s11, s93, s0
	v_sub_f32_e32 v12, v2, v6
	v_frexp_exp_i32_f64_e32 v14, v[0:1]
	v_cmp_gt_f32_e64 s[0:1], s14, v7
	v_sub_f32_e64 v13, -v22, v2
	ds_write_b128 v160, v[8:11]
	v_add_f32_e32 v8, 1.0, v12
	v_subbrev_co_u32_e64 v14, s[0:1], 0, v14, s[0:1]
	v_add_f32_e32 v7, v13, v8
	v_sub_u32_e32 v8, 0, v14
	v_ldexp_f32 v6, v6, v8
	v_ldexp_f32 v7, v7, v8
	v_add_f32_e32 v8, -1.0, v6
	v_add_f32_e32 v9, 1.0, v6
	v_add_f32_e32 v10, 1.0, v8
	v_add_f32_e32 v11, -1.0, v9
	v_sub_f32_e32 v10, v6, v10
	v_sub_f32_e32 v6, v6, v11
	v_add_f32_e32 v6, v7, v6
	v_add_f32_e32 v15, v9, v6
	v_rcp_f32_e32 v17, v15
	v_add_f32_e32 v10, v7, v10
	v_sub_f32_e32 v7, v15, v9
	v_sub_f32_e32 v16, v6, v7
	v_add_f32_e32 v7, v8, v10
	v_mul_f32_e32 v19, v7, v17
	v_sub_f32_e32 v6, v7, v8
	v_mul_f32_e32 v8, v15, v19
	v_sub_f32_e32 v18, v10, v6
	v_fma_f32 v10, v19, v15, -v8
	v_fmac_f32_e32 v10, v19, v16
	v_add_f32_e32 v6, v8, v10
	v_sub_f32_e32 v9, v7, v6
	v_pk_add_f32 v[12:13], v[6:7], v[8:9] neg_lo:[0,1] neg_hi:[0,1]
	v_mov_b32_e32 v11, v6
	v_pk_add_f32 v[6:7], v[12:13], v[10:11] neg_lo:[0,1] neg_hi:[0,1]
	v_cmp_nlt_f32_e64 s[0:1], 1.0, v22
	v_add_f32_e32 v7, v18, v7
	v_add_f32_e32 v6, v6, v7
	v_add_f32_e32 v7, v9, v6
	v_mul_f32_e32 v18, v17, v7
	v_mul_f32_e32 v8, v15, v18
	v_fma_f32 v10, v18, v15, -v8
	v_fmac_f32_e32 v10, v18, v16
	v_sub_f32_e32 v9, v9, v7
	v_add_f32_e32 v15, v6, v9
	v_add_f32_e32 v6, v8, v10
	v_sub_f32_e32 v9, v7, v6
	v_pk_add_f32 v[12:13], v[6:7], v[8:9] neg_lo:[0,1] neg_hi:[0,1]
	v_mov_b32_e32 v11, v6
	v_pk_add_f32 v[6:7], v[12:13], v[10:11] neg_lo:[0,1] neg_hi:[0,1]
	s_lshl_b32 s8, s18, 8
	v_add_f32_e32 v7, v15, v7
	v_add_f32_e32 v6, v6, v7
	v_add_f32_e32 v7, v19, v18
	v_add_f32_e32 v6, v9, v6
	v_sub_f32_e32 v8, v7, v19
	v_mul_f32_e32 v6, v17, v6
	v_sub_f32_e32 v8, v18, v8
	v_add_f32_e32 v8, v8, v6
	v_add_f32_e32 v10, v7, v8
	v_mul_f32_e32 v11, v10, v10
	v_fmamk_f32 v6, v11, 0x3e9b6dac, v161
	v_fmaak_f32 v83, v11, v6, 0x3f2aaada
	v_cvt_f32_i32_e32 v6, v14
	v_sub_f32_e32 v7, v10, v7
	v_sub_f32_e32 v7, v8, v7
	v_ldexp_f32 v12, v7, 1
	v_mul_f32_e32 v7, v10, v11
; #define LAS __attribute__((address_space(3)))
; DI float ret_lg2(const Params& p, int l, int dir, int h) { return log1pf(-exp2f(p.in[12][(l * 2 + dir) * 5 + h])) * 1.4426950408889634f; }
; DI void phase_ret_scan(const Params& p, int l, LAS unsigned char* lds) {
;     ...
;         const float lg = ret_lg2(p, l, dir, h), gL = exp2f(lg * 128.f);
;         float wt[4][8];
; #pragma unroll
;         for (int ks = 0; ks < 4; ++ks)
; #pragma unroll
;             for (int e = 0; e < 8; ++e) { const int pp = ks * 32 + q4 * 8 + e; wt[ks][e] = exp2f(lg * (float)(dir == 0 ? 127 - pp : pp)); }
;         const bf16_t* kt = (const bf16_t*)(ws + WS_KTR) + ((size_t)b * 640 + h * 128 + dkb * 16 + r16) * RB + q4 * 8;
;         const LAS unsigned char* vl = lds + r16 * VRS + q4 * 16;
;         bf16_t* sb = (bf16_t*)(ws + WS_S) + ((size_t)((b * 5 + h) * 2 + dir) * 18) * 16384 + (dvb * 16 + r16) * 128 + dkb * 16 + q4 * 4;
;         f32x4 st = (f32x4){0.f, 0.f, 0.f, 0.f};
;         bf16x8 ca[4];
;         { const int c0 = dir == 0 ? 0 : 1;
; #pragma unroll
;           for (int ks = 0; ks < 4; ++ks) ca[ks] = *(const bf16x8*)(kt + c0 * 128 + ks * 32); }
	v_ldexp_f32 v9, v10, 1
	v_pk_mul_f32 v[10:11], v[6:7], v[82:83]
	v_lshl_add_u64 v[4:5], v[84:85], 0, s[8:9]
	v_fma_f32 v8, v6, s15, -v10
	v_fmac_f32_e32 v8, 0xb102e308, v6
	v_pk_add_f32 v[6:7], v[10:11], v[8:9]
	global_load_dwordx4 v[0:3], v[4:5], off
	v_sub_f32_e32 v9, v7, v9
	v_sub_f32_e32 v9, v11, v9
	v_add_f32_e32 v13, v12, v9
	v_mov_b32_e32 v12, v10
	v_pk_add_f32 v[10:11], v[6:7], v[10:11] neg_lo:[0,1] neg_hi:[0,1]
	v_pk_add_f32 v[14:15], v[6:7], v[12:13]
	v_mov_b32_e32 v9, v6
	v_mov_b32_e32 v11, v15
	v_pk_add_f32 v[16:17], v[8:9], v[10:11] neg_lo:[0,1] neg_hi:[0,1]
	v_pk_add_f32 v[8:9], v[8:9], v[10:11]
	v_mov_b32_e32 v20, v7
	v_pk_add_f32 v[10:11], v[8:9], v[6:7] op_sel:[1,0] op_sel_hi:[0,1] neg_lo:[0,1] neg_hi:[0,1]
	v_pk_add_f32 v[18:19], v[14:15], v[10:11] op_sel_hi:[1,0] neg_lo:[0,1] neg_hi:[0,1]
	v_mov_b32_e32 v14, v15
	v_mov_b32_e32 v15, v9
	v_mov_b32_e32 v21, v10
	v_pk_add_f32 v[10:11], v[14:15], v[20:21] neg_lo:[0,1] neg_hi:[0,1]
	v_mov_b32_e32 v12, v13
	v_mov_b32_e32 v13, v6
	v_pk_add_f32 v[6:7], v[12:13], v[10:11] neg_lo:[0,1] neg_hi:[0,1]
	v_mov_b32_e32 v18, v16
	v_pk_add_f32 v[10:11], v[18:19], v[6:7]
	v_mov_b32_e32 v17, v9
	v_pk_add_f32 v[12:13], v[10:11], v[10:11] op_sel:[0,1] op_sel_hi:[1,0]
	v_mov_b32_e32 v81, v41
	v_pk_add_f32 v[8:9], v[8:9], v[12:13] op_sel:[1,0] op_sel_hi:[0,1]
	v_mov_b32_e32 v11, v8
	v_pk_add_f32 v[14:15], v[10:11], v[16:17] neg_lo:[0,1] neg_hi:[0,1]
	v_mov_b32_e32 v7, v12
	v_sub_f32_e32 v9, v10, v14
	v_pk_add_f32 v[6:7], v[6:7], v[14:15] neg_lo:[0,1] neg_hi:[0,1]
	v_sub_f32_e32 v9, v16, v9
	v_add_f32_e32 v6, v6, v9
	v_add_f32_e32 v6, v6, v7
	v_add_f32_e32 v6, v8, v6
	v_cndmask_b32_e64 v6, v163, v6, s[0:1]
	v_cmp_neq_f32_e64 s[0:1], 1.0, v22
	s_mov_b32 s8, 0
	s_nop 0
	v_cndmask_b32_e64 v6, v164, v6, s[0:1]
	v_cmp_lt_f32_e64 s[0:1], |v22|, s16
	s_nop 1
	v_cndmask_b32_e64 v6, v6, -v22, s[0:1]
	v_mul_f32_e32 v18, 0x3fb8aa3b, v6
	v_cndmask_b32_e32 v6, v87, v89, vcc
	v_cvt_f32_ubyte0_e32 v6, v6
	v_mul_f32_e32 v7, v18, v6
	v_cmp_gt_f32_e64 s[0:1], s13, v7
	v_mul_f32_e32 v19, 0x43000000, v18
	v_mov_b32_e32 v22, 0
	v_cndmask_b32_e64 v7, 0, v162, s[0:1]
	v_fmac_f32_e32 v7, v18, v6
	v_exp_f32_e32 v6, v7
	v_cndmask_b32_e64 v7, 0, v165, s[0:1]
	v_mov_b32_e32 v23, v22
	v_mov_b32_e32 v24, v22
	v_ldexp_f32 v26, v6, v7
	v_cndmask_b32_e32 v6, v90, v91, vcc
	v_cvt_f32_ubyte0_e32 v6, v6
	v_mul_f32_e32 v7, v18, v6
	v_cmp_gt_f32_e64 s[0:1], s13, v7
	v_mov_b32_e32 v25, v22
	s_nop 0
	v_cndmask_b32_e64 v7, 0, v162, s[0:1]
	v_fmac_f32_e32 v7, v18, v6
	v_exp_f32_e32 v6, v7
	v_cndmask_b32_e32 v7, v92, v93, vcc
	v_cvt_f32_ubyte0_e32 v7, v7
	v_mul_f32_e32 v8, v18, v7
	v_cmp_gt_f32_e64 s[2:3], s13, v8
	s_nop 1
	v_cndmask_b32_e64 v8, 0, v162, s[2:3]
	v_fmac_f32_e32 v8, v18, v7
	v_exp_f32_e32 v7, v8
	v_cndmask_b32_e64 v8, 0, v165, s[0:1]
	v_ldexp_f32 v27, v6, v8
	v_cndmask_b32_e64 v6, 0, v165, s[2:3]
	v_ldexp_f32 v28, v7, v6
	v_cndmask_b32_e32 v6, v94, v95, vcc
	v_cvt_f32_ubyte0_e32 v6, v6
	v_mul_f32_e32 v7, v18, v6
	v_cmp_gt_f32_e64 s[0:1], s13, v7
	s_nop 1
	v_cndmask_b32_e64 v7, 0, v162, s[0:1]
	v_fmac_f32_e32 v7, v18, v6
	v_exp_f32_e32 v6, v7
	v_cndmask_b32_e32 v7, v96, v97, vcc
	v_cvt_f32_ubyte0_e32 v7, v7
	v_mul_f32_e32 v8, v18, v7
	v_cmp_gt_f32_e64 s[2:3], s13, v8
	s_nop 1
	v_cndmask_b32_e64 v8, 0, v162, s[2:3]
	v_fmac_f32_e32 v8, v18, v7
	v_exp_f32_e32 v7, v8
	v_cndmask_b32_e64 v8, 0, v165, s[0:1]
	v_ldexp_f32 v29, v6, v8
	v_cndmask_b32_e64 v6, 0, v165, s[2:3]
	v_ldexp_f32 v30, v7, v6
	v_cndmask_b32_e32 v6, v98, v99, vcc
	v_cvt_f32_ubyte0_e32 v6, v6
	v_mul_f32_e32 v7, v18, v6
	v_cmp_gt_f32_e64 s[0:1], s13, v7
	s_nop 1
	v_cndmask_b32_e64 v7, 0, v162, s[0:1]
	v_fmac_f32_e32 v7, v18, v6
	v_exp_f32_e32 v6, v7
	v_cndmask_b32_e32 v7, v100, v101, vcc
	v_cvt_f32_ubyte0_e32 v7, v7
	v_mul_f32_e32 v8, v18, v7
	v_cmp_gt_f32_e64 s[2:3], s13, v8
	s_nop 1
	v_cndmask_b32_e64 v8, 0, v162, s[2:3]
	v_fmac_f32_e32 v8, v18, v7
	v_exp_f32_e32 v7, v8
	v_cndmask_b32_e64 v8, 0, v165, s[0:1]
	v_ldexp_f32 v31, v6, v8
	v_cndmask_b32_e64 v6, 0, v165, s[2:3]
	v_ldexp_f32 v32, v7, v6
	v_cndmask_b32_e32 v6, v102, v103, vcc
	v_cvt_f32_ubyte0_e32 v6, v6
	v_mul_f32_e32 v7, v18, v6
	v_cmp_gt_f32_e64 s[0:1], s13, v7
	s_nop 1
	v_cndmask_b32_e64 v7, 0, v162, s[0:1]
	v_fmac_f32_e32 v7, v18, v6
	v_exp_f32_e32 v6, v7
	v_cndmask_b32_e32 v7, v104, v105, vcc
	v_cvt_f32_ubyte0_e32 v7, v7
	v_mul_f32_e32 v8, v18, v7
	v_cmp_gt_f32_e64 s[2:3], s13, v8
	s_nop 1
	v_cndmask_b32_e64 v8, 0, v162, s[2:3]
	v_fmac_f32_e32 v8, v18, v7
	v_exp_f32_e32 v7, v8
	v_cndmask_b32_e64 v8, 0, v165, s[0:1]
	v_ldexp_f32 v33, v6, v8
	v_cndmask_b32_e64 v6, 0, v165, s[2:3]
	v_ldexp_f32 v34, v7, v6
	v_cndmask_b32_e32 v6, v106, v107, vcc
	v_cvt_f32_ubyte0_e32 v6, v6
	v_mul_f32_e32 v7, v18, v6
	v_cmp_gt_f32_e64 s[0:1], s13, v7
	s_nop 1
	v_cndmask_b32_e64 v7, 0, v162, s[0:1]
	v_fmac_f32_e32 v7, v18, v6
	v_exp_f32_e32 v6, v7
	v_cndmask_b32_e32 v7, v108, v109, vcc
	v_cvt_f32_ubyte0_e32 v7, v7
	v_mul_f32_e32 v8, v18, v7
	v_cmp_gt_f32_e64 s[2:3], s13, v8
	s_nop 1
	v_cndmask_b32_e64 v8, 0, v162, s[2:3]
	v_fmac_f32_e32 v8, v18, v7
	v_exp_f32_e32 v7, v8
	v_cndmask_b32_e64 v8, 0, v165, s[0:1]
	v_ldexp_f32 v35, v6, v8
	v_cndmask_b32_e64 v6, 0, v165, s[2:3]
	v_ldexp_f32 v83, v7, v6
	v_cndmask_b32_e32 v6, v110, v111, vcc
	v_cvt_f32_ubyte0_e32 v6, v6
	v_mul_f32_e32 v7, v18, v6
	v_cmp_gt_f32_e64 s[0:1], s13, v7
	s_nop 1
	v_cndmask_b32_e64 v7, 0, v162, s[0:1]
	v_fmac_f32_e32 v7, v18, v6
	v_exp_f32_e32 v6, v7
	v_cndmask_b32_e32 v7, v112, v113, vcc
	v_cvt_f32_ubyte0_e32 v7, v7
	v_mul_f32_e32 v8, v18, v7
	v_cmp_gt_f32_e64 s[2:3], s13, v8
	s_nop 1
	v_cndmask_b32_e64 v8, 0, v162, s[2:3]
	v_fmac_f32_e32 v8, v18, v7
; #define LAS __attribute__((address_space(3)))
; DI void phase_ret_scan(const Params& p, int l, LAS unsigned char* lds) {
;     ...
;         for (int ks = 0; ks < 4; ++ks)
; #pragma unroll
;             for (int e = 0; e < 8; ++e) { const int pp = ks * 32 + q4 * 8 + e; wt[ks][e] = exp2f(lg * (float)(dir == 0 ? 127 - pp : pp)); }
;         const bf16_t* kt = (const bf16_t*)(ws + WS_KTR) + ((size_t)b * 640 + h * 128 + dkb * 16 + r16) * RB + q4 * 8;
;         const LAS unsigned char* vl = lds + r16 * VRS + q4 * 16;
;         bf16_t* sb = (bf16_t*)(ws + WS_S) + ((size_t)((b * 5 + h) * 2 + dir) * 18) * 16384 + (dvb * 16 + r16) * 128 + dkb * 16 + q4 * 4;
;         f32x4 st = (f32x4){0.f, 0.f, 0.f, 0.f};
;         bf16x8 ca[4];
;         { const int c0 = dir == 0 ? 0 : 1;
; #pragma unroll
;           for (int ks = 0; ks < 4; ++ks) ca[ks] = *(const bf16x8*)(kt + c0 * 128 + ks * 32); }
;         __syncthreads();
; #pragma unroll 2
;         for (int step = 0; step < 18; ++step) {
;             const int c = dir == 0 ? step : (step < 2 ? 1 - step : 19 - step);
;             const int sn = step < 17 ? step + 1 : 17;
;             const int cn = dir == 0 ? sn : (sn < 2 ? 1 - sn : 19 - sn);
;             bf16x8 na_[4];
; #pragma unroll
;             for (int ks = 0; ks < 4; ++ks) na_[ks] = *(const bf16x8*)(kt + cn * 128 + ks * 32);
	v_exp_f32_e32 v7, v8
	v_cndmask_b32_e64 v8, 0, v165, s[0:1]
	v_ldexp_f32 v166, v6, v8
	v_cndmask_b32_e64 v6, 0, v165, s[2:3]
	v_ldexp_f32 v167, v7, v6
	v_cndmask_b32_e32 v6, v114, v115, vcc
	v_cvt_f32_ubyte0_e32 v6, v6
	v_mul_f32_e32 v7, v18, v6
	v_cmp_gt_f32_e64 s[0:1], s13, v7
	s_nop 1
	v_cndmask_b32_e64 v7, 0, v162, s[0:1]
	v_fmac_f32_e32 v7, v18, v6
	v_exp_f32_e32 v6, v7
	v_cndmask_b32_e32 v7, v116, v117, vcc
	v_cvt_f32_ubyte0_e32 v7, v7
	v_mul_f32_e32 v8, v18, v7
	v_cmp_gt_f32_e64 s[2:3], s13, v8
	s_nop 1
	v_cndmask_b32_e64 v8, 0, v162, s[2:3]
	v_fmac_f32_e32 v8, v18, v7
	v_exp_f32_e32 v7, v8
	v_cndmask_b32_e64 v8, 0, v165, s[0:1]
	v_ldexp_f32 v168, v6, v8
	v_cndmask_b32_e64 v6, 0, v165, s[2:3]
	v_ldexp_f32 v169, v7, v6
	v_cndmask_b32_e32 v6, v118, v119, vcc
	v_cvt_f32_ubyte0_e32 v6, v6
	v_mul_f32_e32 v7, v18, v6
	v_cmp_gt_f32_e64 s[0:1], s13, v7
	s_nop 1
	v_cndmask_b32_e64 v7, 0, v162, s[0:1]
	v_fmac_f32_e32 v7, v18, v6
	v_exp_f32_e32 v6, v7
	v_cndmask_b32_e32 v7, v120, v121, vcc
	v_cvt_f32_ubyte0_e32 v7, v7
	v_mul_f32_e32 v8, v18, v7
	v_cmp_gt_f32_e64 s[2:3], s13, v8
	s_nop 1
	v_cndmask_b32_e64 v8, 0, v162, s[2:3]
	v_fmac_f32_e32 v8, v18, v7
	v_exp_f32_e32 v7, v8
	v_cndmask_b32_e64 v8, 0, v165, s[0:1]
	v_ldexp_f32 v170, v6, v8
	v_cndmask_b32_e64 v6, 0, v165, s[2:3]
	v_ldexp_f32 v171, v7, v6
	v_cndmask_b32_e32 v6, v122, v123, vcc
	v_cvt_f32_ubyte0_e32 v6, v6
	v_mul_f32_e32 v7, v18, v6
	v_cmp_gt_f32_e64 s[0:1], s13, v7
	s_nop 1
	v_cndmask_b32_e64 v7, 0, v162, s[0:1]
	v_fmac_f32_e32 v7, v18, v6
	v_exp_f32_e32 v6, v7
	v_cndmask_b32_e32 v7, v124, v125, vcc
	v_cvt_f32_ubyte0_e32 v7, v7
	v_mul_f32_e32 v8, v18, v7
	v_cmp_gt_f32_e64 s[2:3], s13, v8
	s_nop 1
	v_cndmask_b32_e64 v8, 0, v162, s[2:3]
	v_fmac_f32_e32 v8, v18, v7
	v_exp_f32_e32 v7, v8
	v_cndmask_b32_e64 v8, 0, v165, s[0:1]
	v_ldexp_f32 v172, v6, v8
	v_cndmask_b32_e64 v6, 0, v165, s[2:3]
	v_ldexp_f32 v173, v7, v6
	v_cndmask_b32_e32 v6, v126, v127, vcc
	v_cvt_f32_ubyte0_e32 v6, v6
	v_mul_f32_e32 v7, v18, v6
	v_cmp_gt_f32_e64 s[0:1], s13, v7
	s_nop 1
	v_cndmask_b32_e64 v7, 0, v162, s[0:1]
	v_fmac_f32_e32 v7, v18, v6
	v_exp_f32_e32 v6, v7
	v_cndmask_b32_e32 v7, v128, v129, vcc
	v_cvt_f32_ubyte0_e32 v7, v7
	v_mul_f32_e32 v8, v18, v7
	v_cmp_gt_f32_e64 s[2:3], s13, v8
	s_nop 1
	v_cndmask_b32_e64 v8, 0, v162, s[2:3]
	v_fmac_f32_e32 v8, v18, v7
	v_exp_f32_e32 v7, v8
	v_cndmask_b32_e64 v8, 0, v165, s[0:1]
	v_ldexp_f32 v174, v6, v8
	v_cndmask_b32_e64 v6, 0, v165, s[2:3]
	v_ldexp_f32 v175, v7, v6
	v_cndmask_b32_e32 v6, v130, v131, vcc
	v_cvt_f32_ubyte0_e32 v6, v6
	v_mul_f32_e32 v7, v18, v6
	v_cmp_gt_f32_e64 s[0:1], s13, v7
	s_nop 1
	v_cndmask_b32_e64 v7, 0, v162, s[0:1]
	v_fmac_f32_e32 v7, v18, v6
	v_exp_f32_e32 v6, v7
	v_cndmask_b32_e32 v7, v132, v133, vcc
	v_cvt_f32_ubyte0_e32 v7, v7
	v_mul_f32_e32 v8, v18, v7
	v_cmp_gt_f32_e64 s[2:3], s13, v8
	s_nop 1
	v_cndmask_b32_e64 v8, 0, v162, s[2:3]
	v_fmac_f32_e32 v8, v18, v7
	v_exp_f32_e32 v7, v8
	v_cndmask_b32_e64 v8, 0, v165, s[0:1]
	v_ldexp_f32 v176, v6, v8
	v_cndmask_b32_e64 v6, 0, v165, s[2:3]
	v_ldexp_f32 v177, v7, v6
	v_cndmask_b32_e32 v6, v134, v135, vcc
	v_cvt_f32_ubyte0_e32 v6, v6
	v_mul_f32_e32 v7, v18, v6
	v_cmp_gt_f32_e64 s[0:1], s13, v7
	s_nop 1
	v_cndmask_b32_e64 v7, 0, v162, s[0:1]
	v_fmac_f32_e32 v7, v18, v6
	v_exp_f32_e32 v6, v7
	v_cndmask_b32_e32 v7, v136, v137, vcc
	v_cvt_f32_ubyte0_e32 v7, v7
	v_mul_f32_e32 v8, v18, v7
	v_cmp_gt_f32_e64 s[2:3], s13, v8
	s_nop 1
	v_cndmask_b32_e64 v8, 0, v162, s[2:3]
	v_fmac_f32_e32 v8, v18, v7
	v_exp_f32_e32 v7, v8
	v_cndmask_b32_e64 v8, 0, v165, s[0:1]
	v_ldexp_f32 v178, v6, v8
	v_cndmask_b32_e64 v6, 0, v165, s[2:3]
	v_ldexp_f32 v179, v7, v6
	v_cndmask_b32_e32 v6, v138, v139, vcc
	v_cvt_f32_ubyte0_e32 v6, v6
	v_mul_f32_e32 v7, v18, v6
	v_cmp_gt_f32_e64 s[0:1], s13, v7
	s_nop 1
	v_cndmask_b32_e64 v7, 0, v162, s[0:1]
	v_fmac_f32_e32 v7, v18, v6
	v_exp_f32_e32 v16, v7
	global_load_dwordx4 v[12:15], v[4:5], off offset:64
	global_load_dwordx4 v[8:11], v[4:5], off offset:128
	s_nop 0
	global_load_dwordx4 v[4:7], v[4:5], off offset:192
	v_lshlrev_b32_e32 v254, 4, v202
	v_add_u32_e32 v254, 0x14000, v254
	ds_write_b128 v254, v[92:95]
	ds_write_b128 v254, v[96:99] offset:8192
	ds_write_b128 v254, v[100:103] offset:16384
	ds_write_b128 v254, v[104:107] offset:24576
	s_waitcnt lgkmcnt(0)
	s_and_b64 s[100:101], vcc, exec
	s_cselect_b32 s98, 1, 0
	s_lshl_b32 s98, s98, 8
	s_mov_b32 s99, 0
	v_lshl_add_u64 v[250:251], s[98:99], 0, v[84:85]
	global_load_dwordx4 v[92:95], v[250:251], off
	global_load_dwordx4 v[96:99], v[250:251], off offset:64
	global_load_dwordx4 v[100:103], v[250:251], off offset:128
	global_load_dwordx4 v[104:107], v[250:251], off offset:192
	s_and_b64 s[100:101], vcc, exec
	s_cselect_b32 s98, 2, 17
	s_lshl_b32 s98, s98, 8
	v_lshl_add_u64 v[250:251], s[98:99], 0, v[84:85]
	global_load_dwordx4 v[234:237], v[250:251], off
	global_load_dwordx4 v[238:241], v[250:251], off offset:64
	global_load_dwordx4 v[242:245], v[250:251], off offset:128
	global_load_dwordx4 v[246:249], v[250:251], off offset:192
	v_cndmask_b32_e64 v17, 0, v165, s[0:1]
	s_waitcnt lgkmcnt(0)
	v_ldexp_f32 v180, v16, v17
	v_cndmask_b32_e32 v16, v140, v141, vcc
	v_cvt_f32_ubyte0_e32 v16, v16
	v_mul_f32_e32 v17, v18, v16
	v_cmp_gt_f32_e64 s[0:1], s13, v17
	s_barrier
; #define LAS __attribute__((address_space(3)))
; DI void phase_ret_scan(const Params& p, int l, LAS unsigned char* lds) {
;     ...
;         for (int ks = 0; ks < 4; ++ks)
; #pragma unroll
;             for (int e = 0; e < 8; ++e) { const int pp = ks * 32 + q4 * 8 + e; wt[ks][e] = exp2f(lg * (float)(dir == 0 ? 127 - pp : pp)); }
;         const bf16_t* kt = (const bf16_t*)(ws + WS_KTR) + ((size_t)b * 640 + h * 128 + dkb * 16 + r16) * RB + q4 * 8;
;         const LAS unsigned char* vl = lds + r16 * VRS + q4 * 16;
;         bf16_t* sb = (bf16_t*)(ws + WS_S) + ((size_t)((b * 5 + h) * 2 + dir) * 18) * 16384 + (dvb * 16 + r16) * 128 + dkb * 16 + q4 * 4;
;         f32x4 st = (f32x4){0.f, 0.f, 0.f, 0.f};
;         bf16x8 ca[4];
;         { const int c0 = dir == 0 ? 0 : 1;
; #pragma unroll
;           for (int ks = 0; ks < 4; ++ks) ca[ks] = *(const bf16x8*)(kt + c0 * 128 + ks * 32); }
;         __syncthreads();
; #pragma unroll 2
;         for (int step = 0; step < 18; ++step) {
	s_nop 0
	v_cndmask_b32_e64 v17, 0, v162, s[0:1]
	v_fmac_f32_e32 v17, v18, v16
	v_exp_f32_e32 v16, v17
	v_cndmask_b32_e32 v17, v142, v143, vcc
	v_cvt_f32_ubyte0_e32 v17, v17
	v_mul_f32_e32 v20, v18, v17
	v_cmp_gt_f32_e64 s[2:3], s13, v20
	s_nop 1
	v_cndmask_b32_e64 v20, 0, v162, s[2:3]
	v_fmac_f32_e32 v20, v18, v17
	v_exp_f32_e32 v17, v20
	v_cndmask_b32_e64 v20, 0, v165, s[0:1]
	v_ldexp_f32 v181, v16, v20
	v_cndmask_b32_e64 v16, 0, v165, s[2:3]
	v_ldexp_f32 v182, v17, v16
	v_cndmask_b32_e32 v16, v144, v145, vcc
	v_cvt_f32_ubyte0_e32 v16, v16
	v_mul_f32_e32 v17, v18, v16
	v_cmp_gt_f32_e64 s[0:1], s13, v17
	s_nop 1
	v_cndmask_b32_e64 v17, 0, v162, s[0:1]
	v_fmac_f32_e32 v17, v18, v16
	v_exp_f32_e32 v16, v17
	v_cndmask_b32_e32 v17, v146, v147, vcc
	v_cvt_f32_ubyte0_e32 v17, v17
	v_mul_f32_e32 v20, v18, v17
	v_cmp_gt_f32_e64 s[2:3], s13, v20
	s_nop 1
	v_cndmask_b32_e64 v20, 0, v162, s[2:3]
	v_fmac_f32_e32 v20, v18, v17
	v_exp_f32_e32 v17, v20
	v_cndmask_b32_e64 v20, 0, v165, s[0:1]
	v_ldexp_f32 v183, v16, v20
	v_cndmask_b32_e64 v16, 0, v165, s[2:3]
	v_ldexp_f32 v184, v17, v16
	v_cndmask_b32_e32 v16, v148, v149, vcc
	v_cvt_f32_ubyte0_e32 v16, v16
	v_mul_f32_e32 v17, v18, v16
	v_cmp_gt_f32_e64 s[0:1], s13, v17
	s_nop 1
	v_cndmask_b32_e64 v17, 0, v162, s[0:1]
	v_fmac_f32_e32 v17, v18, v16
	v_exp_f32_e32 v16, v17
	v_cndmask_b32_e32 v17, v150, v151, vcc
	v_cvt_f32_ubyte0_e32 v17, v17
	v_mul_f32_e32 v20, v18, v17
	v_cmp_gt_f32_e64 s[2:3], s13, v20
	s_nop 1
	v_cndmask_b32_e64 v20, 0, v162, s[2:3]
	v_fmac_f32_e32 v20, v18, v17
	v_exp_f32_e32 v17, v20
	v_cndmask_b32_e64 v20, 0, v165, s[0:1]
	v_cmp_gt_f32_e64 s[0:1], s13, v19
	v_ldexp_f32 v185, v16, v20
	v_cndmask_b32_e64 v16, 0, v165, s[2:3]
	v_cndmask_b32_e64 v19, 0, v162, s[0:1]
	v_fmac_f32_e32 v19, 0x43000000, v18
	v_exp_f32_e32 v18, v19
	v_ldexp_f32 v186, v17, v16
	v_or_b32_e32 v16, s17, v86
	v_lshlrev_b32_e32 v40, 8, v16
	s_and_b64 s[0:1], s[0:1], exec
	v_lshl_add_u64 v[16:17], s[10:11], 0, v[40:41]
	s_cselect_b32 s0, 0xffffffc0, 0
	v_lshl_add_u64 v[16:17], v[36:37], 1, v[16:17]
	v_ldexp_f32 v18, v18, s0
	v_lshl_add_u64 v[16:17], v[16:17], 0, v[80:81]
	v_mov_b32_e32 v20, v18
	v_mov_b32_e32 v21, v18
	s_mov_b32 s0, 0
	s_waitcnt vmcnt(8)
